# v11 plus: remaining LDS-DMA loads (P2/P3 and their +128 B repeats in P6/P7, M0 compensated for the instruction offset) in scalar-base form: no VALU address math left in the K-loop
# speedup vs baseline: 1.0065x; 1.0036x over previous
; #define PG8_STAGE(bufoff, gbase, voff) do { _Pragma("unroll") for (int _i = 0; _i < 2; ++_i) \
;         __builtin_amdgcn_global_load_lds((const unsigned*)((const char*)(gbase) + (voff)[_i]), (LAS unsigned*)(lds + (bufoff) + ldsw + _i * 8192), 16, 0, 0); } while (0)
; #define PG8_LDA(dst, b, h) do { _Pragma("unroll") for (int m = 0; m < 4; ++m) _Pragma("unroll") for (int k = 0; k < 2; ++k) dst[m][k] = *(const LAS bf16x8*)(lds + PG8_SA(b, h) + aoff + m * 2048 + k * 1024); } while (0)
; #define PG8_LDB(dst, b, h) do { _Pragma("unroll") for (int n = 0; n < 2; ++n) _Pragma("unroll") for (int k = 0; k < 2; ++k) dst[n][k] = *(const LAS bf16x8*)(lds + PG8_SB(b, h) + boff + n * 2048 + k * 1024); } while (0)
; #define PG8_MMA(ai, bj, At, Bt) do { __builtin_amdgcn_s_setprio(1); _Pragma("unroll") for (int m = 0; m < 4; ++m) _Pragma("unroll") for (int n = 0; n < 2; ++n) _Pragma("unroll") for (int k = 0; k < 2; ++k) \
;         acc[ai][bj][m][n] = __builtin_amdgcn_mfma_f32_16x16x32_bf16(Bt[n][k], At[m][k], acc[ai][bj][m][n], 0, 0, 0); __builtin_amdgcn_s_setprio(0); } while (0)
; #define PG8_WAIT_V(n) asm volatile("s_waitcnt vmcnt(" #n ")" ::: "memory")
; #define PG8_WAIT_L(n) asm volatile("s_waitcnt lgkmcnt(" #n ")" ::: "memory")
; #define PG8_BAR __builtin_amdgcn_s_barrier()
; template <class Epi, class Sched>
; __device__ __forceinline__ void gemm_phase(LAS unsigned char* lds, const Gemm g, const Sched& S, const Epi& E) {
;     ...
;             const bool last = (t == nt - 2);
;             const char* a1 = cA + (size_t)(t + 1) * kstep;
;             const char* a2 = last ? nA : cA + (size_t)(t + 2) * kstep; const char* b2 = last ? nB : cB + (size_t)(t + 2) * kstep;
;             const char* a3 = a2 + kstep; const char* b3 = b2 + kstep;
;             PG8_LDB(B0, 0, 0); PG8_SCHED; PG8_LDA(At, 0, 0); PG8_STAGE(PG8_SA(1, 1), a1 + hstep, voffA);
;             PG8_WAIT_L(8); PG8_BAR; PG8_WAIT_L(0); PG8_MMA(0, 0, At, B0); PG8_BAR; PG8_SCHED;
;             PG8_LDB(B1, 0, 1); PG8_STAGE(PG8_SB(0, 0), b2, voffB);
;             PG8_BAR; PG8_WAIT_L(0); PG8_MMA(0, 1, At, B1); PG8_BAR;
;             PG8_LDA(At, 0, 1); PG8_STAGE(PG8_SA(0, 0), a2, voffA);
;             PG8_BAR; PG8_WAIT_L(0); PG8_MMA(1, 0, At, B0); PG8_BAR; PG8_SCHED;
;             PG8_STAGE(PG8_SB(0, 1), b2 + hstep, voffB);
;             PG8_WAIT_V(6); PG8_BAR; PG8_MMA(1, 1, At, B1); PG8_BAR;
.LBB0_165:
	s_add_u32 s24, s38, 0xfffc0080
	s_addc_u32 s25, s39, -1
	s_add_i32 vcc_hi, 0, 0x10000
	v_add_u32_e32 v166, vcc_hi, v167
	s_cmp_eq_u32 s50, 12
	s_cselect_b32 s61, s34, s25
	s_cselect_b32 s60, s45, s24
	s_cselect_b32 s49, s43, s35
	s_cselect_b32 s48, s79, vcc_lo
	s_add_i32 m0, s93, 0xc000
	ds_read_b128 v[214:217], v169 offset:6144
	ds_read_b128 v[218:221], v169 offset:7168
	global_load_lds_dwordx4 v140, s[38:39]
	s_add_i32 m0, s93, 0xe000
	s_nop 0
	global_load_lds_dwordx4 v138, s[38:39]
	s_waitcnt lgkmcnt(8)
	s_barrier
	s_waitcnt lgkmcnt(0)
	s_setprio 1
	s_waitcnt lgkmcnt(0)
	v_mfma_f32_16x16x32_bf16 v[126:129], v[142:145], v[190:193], v[126:129]
	v_mfma_f32_16x16x32_bf16 v[126:129], v[162:165], v[194:197], v[126:129]
	v_mfma_f32_16x16x32_bf16 v[122:125], v[182:185], v[190:193], v[122:125]
	v_mfma_f32_16x16x32_bf16 v[122:125], v[186:189], v[194:197], v[122:125]
	v_mfma_f32_16x16x32_bf16 v[110:113], v[142:145], v[198:201], v[110:113]
	v_mfma_f32_16x16x32_bf16 v[110:113], v[162:165], v[202:205], v[110:113]
	v_mfma_f32_16x16x32_bf16 v[106:109], v[182:185], v[198:201], v[106:109]
	v_mfma_f32_16x16x32_bf16 v[106:109], v[186:189], v[202:205], v[106:109]
	v_mfma_f32_16x16x32_bf16 v[94:97], v[142:145], v[206:209], v[94:97]
	v_mfma_f32_16x16x32_bf16 v[94:97], v[162:165], v[210:213], v[94:97]
	v_mfma_f32_16x16x32_bf16 v[90:93], v[182:185], v[206:209], v[90:93]
	v_mfma_f32_16x16x32_bf16 v[90:93], v[186:189], v[210:213], v[90:93]
	v_mfma_f32_16x16x32_bf16 v[78:81], v[142:145], v[214:217], v[78:81]
	v_mfma_f32_16x16x32_bf16 v[78:81], v[162:165], v[218:221], v[78:81]
	v_mfma_f32_16x16x32_bf16 v[74:77], v[182:185], v[214:217], v[74:77]
	s_barrier
	v_mfma_f32_16x16x32_bf16 v[74:77], v[186:189], v[218:221], v[74:77]
	s_setprio 0
	s_add_i32 s51, 0, 0x14000
	s_add_i32 s24, vcc_hi, s86
	v_add_u32_e32 v166, s51, v167
	s_mov_b32 m0, s24
	ds_read_b128 v[222:225], v166
	ds_read_b128 v[226:229], v166 offset:1024
	ds_read_b128 v[230:233], v166 offset:2048
	ds_read_b128 v[234:237], v166 offset:3072
	global_load_lds_dwordx4 v134, s[48:49]
	s_add_i32 m0, s24, 0x2000
	s_nop 0
	global_load_lds_dwordx4 v130, s[48:49]
	s_barrier
	s_waitcnt lgkmcnt(0)
	s_setprio 1
	s_waitcnt lgkmcnt(0)
	v_mfma_f32_16x16x32_bf16 v[118:121], v[222:225], v[190:193], v[118:121]
	v_mfma_f32_16x16x32_bf16 v[118:121], v[226:229], v[194:197], v[118:121]
	v_mfma_f32_16x16x32_bf16 v[114:117], v[230:233], v[190:193], v[114:117]
	v_mfma_f32_16x16x32_bf16 v[114:117], v[234:237], v[194:197], v[114:117]
	v_mfma_f32_16x16x32_bf16 v[102:105], v[222:225], v[198:201], v[102:105]
	v_mfma_f32_16x16x32_bf16 v[102:105], v[226:229], v[202:205], v[102:105]
	v_mfma_f32_16x16x32_bf16 v[98:101], v[230:233], v[198:201], v[98:101]
	v_mfma_f32_16x16x32_bf16 v[98:101], v[234:237], v[202:205], v[98:101]
	v_mfma_f32_16x16x32_bf16 v[86:89], v[222:225], v[206:209], v[86:89]
	v_mfma_f32_16x16x32_bf16 v[86:89], v[226:229], v[210:213], v[86:89]
	v_mfma_f32_16x16x32_bf16 v[82:85], v[230:233], v[206:209], v[82:85]
	v_mfma_f32_16x16x32_bf16 v[82:85], v[234:237], v[210:213], v[82:85]
	v_mfma_f32_16x16x32_bf16 v[70:73], v[222:225], v[214:217], v[70:73]
	v_mfma_f32_16x16x32_bf16 v[70:73], v[226:229], v[218:221], v[70:73]
	v_mfma_f32_16x16x32_bf16 v[66:69], v[230:233], v[214:217], v[66:69]
	s_barrier
	v_mfma_f32_16x16x32_bf16 v[66:69], v[234:237], v[218:221], v[66:69]
	s_setprio 0
	s_mov_b32 m0, s93
	s_mov_b64 s[100:101], s[60:61]
	ds_read_b128 v[190:193], v169 offset:16384
	ds_read_b128 v[194:197], v169 offset:17408
	ds_read_b128 v[198:201], v169 offset:18432
	ds_read_b128 v[202:205], v169 offset:19456
	ds_read_b128 v[206:209], v169 offset:20480
	ds_read_b128 v[210:213], v169 offset:21504
	ds_read_b128 v[214:217], v169 offset:22528
	ds_read_b128 v[218:221], v169 offset:23552
	global_load_lds_dwordx4 v136, s[60:61]
	s_mov_b64 s[100:101], s[60:61]
	s_mov_b32 m0, s98
	s_nop 0
	global_load_lds_dwordx4 v132, s[60:61]
	s_waitcnt vmcnt(8)
	s_barrier
	s_waitcnt lgkmcnt(0)
	s_setprio 1
	s_waitcnt lgkmcnt(0)
	v_mfma_f32_16x16x32_bf16 v[62:65], v[142:145], v[190:193], v[62:65]
	v_mfma_f32_16x16x32_bf16 v[62:65], v[162:165], v[194:197], v[62:65]
	v_mfma_f32_16x16x32_bf16 v[58:61], v[182:185], v[190:193], v[58:61]
	v_mfma_f32_16x16x32_bf16 v[58:61], v[186:189], v[194:197], v[58:61]
	v_mfma_f32_16x16x32_bf16 v[46:49], v[142:145], v[198:201], v[46:49]
	v_mfma_f32_16x16x32_bf16 v[46:49], v[162:165], v[202:205], v[46:49]
	v_mfma_f32_16x16x32_bf16 v[42:45], v[182:185], v[198:201], v[42:45]
	v_mfma_f32_16x16x32_bf16 v[42:45], v[186:189], v[202:205], v[42:45]
	v_mfma_f32_16x16x32_bf16 v[30:33], v[142:145], v[206:209], v[30:33]
	v_mfma_f32_16x16x32_bf16 v[30:33], v[162:165], v[210:213], v[30:33]
	v_mfma_f32_16x16x32_bf16 v[26:29], v[182:185], v[206:209], v[26:29]
	v_mfma_f32_16x16x32_bf16 v[26:29], v[186:189], v[210:213], v[26:29]
	v_mfma_f32_16x16x32_bf16 v[14:17], v[142:145], v[214:217], v[14:17]
	v_mfma_f32_16x16x32_bf16 v[14:17], v[162:165], v[218:221], v[14:17]
	v_mfma_f32_16x16x32_bf16 v[10:13], v[182:185], v[214:217], v[10:13]
	s_barrier
	v_mfma_f32_16x16x32_bf16 v[10:13], v[186:189], v[218:221], v[10:13]
	s_setprio 0
	s_add_u32 s24, s48, 0x40000
	s_addc_u32 s25, s49, 0
	s_add_i32 s51, s51, s86
	s_mov_b32 m0, s51
	s_nop 0
	global_load_lds_dwordx4 v134, s[24:25]
	s_add_i32 m0, s51, 0x2000
	s_nop 0
	global_load_lds_dwordx4 v130, s[24:25]
	s_waitcnt vmcnt(6)
	s_barrier
; #define PG8_STAGE(bufoff, gbase, voff) do { _Pragma("unroll") for (int _i = 0; _i < 2; ++_i) \
;         __builtin_amdgcn_global_load_lds((const unsigned*)((const char*)(gbase) + (voff)[_i]), (LAS unsigned*)(lds + (bufoff) + ldsw + _i * 8192), 16, 0, 0); } while (0)
; #define PG8_LDA(dst, b, h) do { _Pragma("unroll") for (int m = 0; m < 4; ++m) _Pragma("unroll") for (int k = 0; k < 2; ++k) dst[m][k] = *(const LAS bf16x8*)(lds + PG8_SA(b, h) + aoff + m * 2048 + k * 1024); } while (0)
; #define PG8_LDB(dst, b, h) do { _Pragma("unroll") for (int n = 0; n < 2; ++n) _Pragma("unroll") for (int k = 0; k < 2; ++k) dst[n][k] = *(const LAS bf16x8*)(lds + PG8_SB(b, h) + boff + n * 2048 + k * 1024); } while (0)
; #define PG8_MMA(ai, bj, At, Bt) do { __builtin_amdgcn_s_setprio(1); _Pragma("unroll") for (int m = 0; m < 4; ++m) _Pragma("unroll") for (int n = 0; n < 2; ++n) _Pragma("unroll") for (int k = 0; k < 2; ++k) \
;         acc[ai][bj][m][n] = __builtin_amdgcn_mfma_f32_16x16x32_bf16(Bt[n][k], At[m][k], acc[ai][bj][m][n], 0, 0, 0); __builtin_amdgcn_s_setprio(0); } while (0)
; #define PG8_WAIT_V(n) asm volatile("s_waitcnt vmcnt(" #n ")" ::: "memory")
; #define PG8_WAIT_L(n) asm volatile("s_waitcnt lgkmcnt(" #n ")" ::: "memory")
; #define PG8_BAR __builtin_amdgcn_s_barrier()
; #define PG8_SCHED __builtin_amdgcn_sched_barrier(0)
; template <class Epi, class Sched>
; __device__ __forceinline__ void gemm_phase(LAS unsigned char* lds, const Gemm g, const Sched& S, const Epi& E) {
;     ...
;             PG8_WAIT_V(6); PG8_BAR; PG8_MMA(1, 1, At, B1); PG8_BAR;
;             PG8_LDB(B0, 1, 0); PG8_SCHED; PG8_LDA(At, 1, 0); PG8_STAGE(PG8_SA(0, 1), a2 + hstep, voffA);
;             PG8_WAIT_L(8); PG8_BAR; PG8_WAIT_L(0); PG8_MMA(0, 0, At, B0); PG8_BAR; PG8_SCHED;
;             PG8_LDB(B1, 1, 1); PG8_STAGE(PG8_SB(1, 0), b3, voffB);
;             PG8_BAR; PG8_WAIT_L(0); PG8_MMA(0, 1, At, B1); PG8_BAR;
	s_setprio 1
	v_add_u32_e32 v249, 0x18000, v167
	v_mfma_f32_16x16x32_bf16 v[54:57], v[222:225], v[190:193], v[54:57]
	ds_read_b128 v[142:145], v249
	ds_read_b128 v[162:165], v249 offset:1024
	v_mfma_f32_16x16x32_bf16 v[54:57], v[226:229], v[194:197], v[54:57]
	ds_read_b128 v[182:185], v249 offset:2048
	ds_read_b128 v[186:189], v249 offset:3072
	v_mfma_f32_16x16x32_bf16 v[50:53], v[230:233], v[190:193], v[50:53]
	ds_read_b128 v[190:193], v169 offset:32768
	v_mfma_f32_16x16x32_bf16 v[50:53], v[234:237], v[194:197], v[50:53]
	ds_read_b128 v[194:197], v169 offset:33792
	v_mfma_f32_16x16x32_bf16 v[38:41], v[222:225], v[198:201], v[38:41]
	v_mfma_f32_16x16x32_bf16 v[38:41], v[226:229], v[202:205], v[38:41]
	v_mfma_f32_16x16x32_bf16 v[34:37], v[230:233], v[198:201], v[34:37]
	ds_read_b128 v[198:201], v169 offset:34816
	v_mfma_f32_16x16x32_bf16 v[34:37], v[234:237], v[202:205], v[34:37]
	ds_read_b128 v[202:205], v169 offset:35840
	v_mfma_f32_16x16x32_bf16 v[22:25], v[222:225], v[206:209], v[22:25]
	v_mfma_f32_16x16x32_bf16 v[22:25], v[226:229], v[210:213], v[22:25]
	v_mfma_f32_16x16x32_bf16 v[18:21], v[230:233], v[206:209], v[18:21]
	ds_read_b128 v[206:209], v169 offset:36864
	v_mfma_f32_16x16x32_bf16 v[18:21], v[234:237], v[210:213], v[18:21]
	ds_read_b128 v[210:213], v169 offset:37888
	v_mfma_f32_16x16x32_bf16 v[6:9], v[222:225], v[214:217], v[6:9]
	v_mfma_f32_16x16x32_bf16 v[6:9], v[226:229], v[218:221], v[6:9]
	v_mfma_f32_16x16x32_bf16 v[2:5], v[230:233], v[214:217], v[2:5]
	s_barrier
	v_mfma_f32_16x16x32_bf16 v[2:5], v[234:237], v[218:221], v[2:5]
	s_setprio 0
	s_add_i32 s51, 0, 0x18000
	v_add_u32_e32 v166, s51, v167
	s_add_u32 s24, s60, 0x40000
	s_addc_u32 s25, s61, 0
	s_mov_b32 m0, s99
	ds_read_b128 v[214:217], v169 offset:38912
	ds_read_b128 v[218:221], v169 offset:39936
	global_load_lds_dwordx4 v136, s[24:25]
	s_mov_b32 m0, s94
	s_nop 0
	global_load_lds_dwordx4 v132, s[24:25]
	s_waitcnt lgkmcnt(8)
	s_barrier
	s_waitcnt lgkmcnt(0)
	s_setprio 1
	s_waitcnt lgkmcnt(0)
	v_mfma_f32_16x16x32_bf16 v[126:129], v[142:145], v[190:193], v[126:129]
	v_mfma_f32_16x16x32_bf16 v[126:129], v[162:165], v[194:197], v[126:129]
	v_mfma_f32_16x16x32_bf16 v[122:125], v[182:185], v[190:193], v[122:125]
	v_mfma_f32_16x16x32_bf16 v[122:125], v[186:189], v[194:197], v[122:125]
	v_mfma_f32_16x16x32_bf16 v[110:113], v[142:145], v[198:201], v[110:113]
	v_mfma_f32_16x16x32_bf16 v[110:113], v[162:165], v[202:205], v[110:113]
	v_mfma_f32_16x16x32_bf16 v[106:109], v[182:185], v[198:201], v[106:109]
	v_mfma_f32_16x16x32_bf16 v[106:109], v[186:189], v[202:205], v[106:109]
	v_mfma_f32_16x16x32_bf16 v[94:97], v[142:145], v[206:209], v[94:97]
	v_mfma_f32_16x16x32_bf16 v[94:97], v[162:165], v[210:213], v[94:97]
	v_mfma_f32_16x16x32_bf16 v[90:93], v[182:185], v[206:209], v[90:93]
	v_mfma_f32_16x16x32_bf16 v[90:93], v[186:189], v[210:213], v[90:93]
	v_mfma_f32_16x16x32_bf16 v[78:81], v[142:145], v[214:217], v[78:81]
	v_mfma_f32_16x16x32_bf16 v[78:81], v[162:165], v[218:221], v[78:81]
	v_mfma_f32_16x16x32_bf16 v[74:77], v[182:185], v[214:217], v[74:77]
	s_barrier
	v_mfma_f32_16x16x32_bf16 v[74:77], v[186:189], v[218:221], v[74:77]
	s_setprio 0
	s_add_i32 s60, 0, 0x1c000
	s_add_i32 s24, s51, s86
	v_add_u32_e32 v166, s60, v167
	s_add_i32 m0, s24, 0xffffff80
	ds_read_b128 v[222:225], v166
	ds_read_b128 v[226:229], v166 offset:1024
	ds_read_b128 v[230:233], v166 offset:2048
	ds_read_b128 v[234:237], v166 offset:3072
	global_load_lds_dwordx4 v134, s[48:49] offset:128
	s_add_i32 m0, s24, 0x1f80
	s_nop 0
	global_load_lds_dwordx4 v130, s[48:49] offset:128
	s_barrier
	s_waitcnt lgkmcnt(0)
	s_setprio 1
	s_waitcnt lgkmcnt(0)
	v_mfma_f32_16x16x32_bf16 v[118:121], v[222:225], v[190:193], v[118:121]
	v_mfma_f32_16x16x32_bf16 v[118:121], v[226:229], v[194:197], v[118:121]
	v_mfma_f32_16x16x32_bf16 v[114:117], v[230:233], v[190:193], v[114:117]
	v_mfma_f32_16x16x32_bf16 v[114:117], v[234:237], v[194:197], v[114:117]
	v_mfma_f32_16x16x32_bf16 v[102:105], v[222:225], v[198:201], v[102:105]
	v_mfma_f32_16x16x32_bf16 v[102:105], v[226:229], v[202:205], v[102:105]
	v_mfma_f32_16x16x32_bf16 v[98:101], v[230:233], v[198:201], v[98:101]
	v_mfma_f32_16x16x32_bf16 v[98:101], v[234:237], v[202:205], v[98:101]
	v_mfma_f32_16x16x32_bf16 v[86:89], v[222:225], v[206:209], v[86:89]
	v_mfma_f32_16x16x32_bf16 v[86:89], v[226:229], v[210:213], v[86:89]
	v_mfma_f32_16x16x32_bf16 v[82:85], v[230:233], v[206:209], v[82:85]
	v_mfma_f32_16x16x32_bf16 v[82:85], v[234:237], v[210:213], v[82:85]
	v_mfma_f32_16x16x32_bf16 v[70:73], v[222:225], v[214:217], v[70:73]
	v_mfma_f32_16x16x32_bf16 v[70:73], v[226:229], v[218:221], v[70:73]
	v_mfma_f32_16x16x32_bf16 v[66:69], v[230:233], v[214:217], v[66:69]
	s_barrier
; #define PG8_STAGE(bufoff, gbase, voff) do { _Pragma("unroll") for (int _i = 0; _i < 2; ++_i) \
;         __builtin_amdgcn_global_load_lds((const unsigned*)((const char*)(gbase) + (voff)[_i]), (LAS unsigned*)(lds + (bufoff) + ldsw + _i * 8192), 16, 0, 0); } while (0)
; #define PG8_LDA(dst, b, h) do { _Pragma("unroll") for (int m = 0; m < 4; ++m) _Pragma("unroll") for (int k = 0; k < 2; ++k) dst[m][k] = *(const LAS bf16x8*)(lds + PG8_SA(b, h) + aoff + m * 2048 + k * 1024); } while (0)
; #define PG8_MMA(ai, bj, At, Bt) do { __builtin_amdgcn_s_setprio(1); _Pragma("unroll") for (int m = 0; m < 4; ++m) _Pragma("unroll") for (int n = 0; n < 2; ++n) _Pragma("unroll") for (int k = 0; k < 2; ++k) \
;         acc[ai][bj][m][n] = __builtin_amdgcn_mfma_f32_16x16x32_bf16(Bt[n][k], At[m][k], acc[ai][bj][m][n], 0, 0, 0); __builtin_amdgcn_s_setprio(0); } while (0)
; #define PG8_WAIT_V(n) asm volatile("s_waitcnt vmcnt(" #n ")" ::: "memory")
; #define PG8_WAIT_L(n) asm volatile("s_waitcnt lgkmcnt(" #n ")" ::: "memory")
; #define PG8_BAR __builtin_amdgcn_s_barrier()
; #define PG8_SCHED __builtin_amdgcn_sched_barrier(0)
; template <class Epi, class Sched>
; __device__ __forceinline__ void gemm_phase(LAS unsigned char* lds, const Gemm g, const Sched& S, const Epi& E) {
;     ...
;             PG8_LDA(At, 1, 1); PG8_STAGE(PG8_SA(1, 0), a3, voffA);
;             PG8_BAR; PG8_WAIT_L(0); PG8_MMA(1, 0, At, B0); PG8_BAR; PG8_SCHED;
;             PG8_STAGE(PG8_SB(1, 1), b3 + hstep, voffB);
;             PG8_WAIT_V(6); PG8_BAR; PG8_MMA(1, 1, At, B1); PG8_BAR;
;         }
	v_mfma_f32_16x16x32_bf16 v[66:69], v[234:237], v[218:221], v[66:69]
	s_setprio 0
	s_add_i32 m0, s95, 0xffffff80
	ds_read_b128 v[190:193], v169 offset:49152
	ds_read_b128 v[194:197], v169 offset:50176
	ds_read_b128 v[198:201], v169 offset:51200
	ds_read_b128 v[202:205], v169 offset:52224
	ds_read_b128 v[206:209], v169 offset:53248
	ds_read_b128 v[210:213], v169 offset:54272
	ds_read_b128 v[214:217], v169 offset:55296
	ds_read_b128 v[218:221], v169 offset:56320
	global_load_lds_dwordx4 v136, s[100:101] offset:128
	s_add_i32 m0, s96, 0xffffff80
	s_nop 0
	global_load_lds_dwordx4 v132, s[100:101] offset:128
	s_waitcnt vmcnt(8)
	s_barrier
	s_waitcnt lgkmcnt(0)
	s_setprio 1
	s_waitcnt lgkmcnt(0)
	v_mfma_f32_16x16x32_bf16 v[62:65], v[142:145], v[190:193], v[62:65]
	v_mfma_f32_16x16x32_bf16 v[62:65], v[162:165], v[194:197], v[62:65]
	v_mfma_f32_16x16x32_bf16 v[58:61], v[182:185], v[190:193], v[58:61]
	v_mfma_f32_16x16x32_bf16 v[58:61], v[186:189], v[194:197], v[58:61]
	v_mfma_f32_16x16x32_bf16 v[46:49], v[142:145], v[198:201], v[46:49]
	v_mfma_f32_16x16x32_bf16 v[46:49], v[162:165], v[202:205], v[46:49]
	v_mfma_f32_16x16x32_bf16 v[42:45], v[182:185], v[198:201], v[42:45]
	v_mfma_f32_16x16x32_bf16 v[42:45], v[186:189], v[202:205], v[42:45]
	v_mfma_f32_16x16x32_bf16 v[30:33], v[142:145], v[206:209], v[30:33]
	v_mfma_f32_16x16x32_bf16 v[30:33], v[162:165], v[210:213], v[30:33]
	v_mfma_f32_16x16x32_bf16 v[26:29], v[182:185], v[206:209], v[26:29]
	v_mfma_f32_16x16x32_bf16 v[26:29], v[186:189], v[210:213], v[26:29]
	v_mfma_f32_16x16x32_bf16 v[14:17], v[142:145], v[214:217], v[14:17]
	v_mfma_f32_16x16x32_bf16 v[14:17], v[162:165], v[218:221], v[14:17]
	v_mfma_f32_16x16x32_bf16 v[10:13], v[182:185], v[214:217], v[10:13]
	s_barrier
	v_mfma_f32_16x16x32_bf16 v[10:13], v[186:189], v[218:221], v[10:13]
	s_setprio 0
	s_add_u32 s24, s48, 0x40080
	s_addc_u32 s25, s49, 0
	s_add_i32 s48, s60, s86
	s_mov_b32 m0, s48
	s_nop 0
	global_load_lds_dwordx4 v134, s[24:25]
	s_add_i32 m0, s48, 0x2000
	s_nop 0
	global_load_lds_dwordx4 v130, s[24:25]
	s_waitcnt vmcnt(6)
	s_barrier
	s_setprio 1
	v_add_u32_e32 v249, 0x10000, v167
	v_mfma_f32_16x16x32_bf16 v[54:57], v[222:225], v[190:193], v[54:57]
	ds_read_b128 v[142:145], v249
	ds_read_b128 v[162:165], v249 offset:1024
	v_mfma_f32_16x16x32_bf16 v[54:57], v[226:229], v[194:197], v[54:57]
	ds_read_b128 v[182:185], v249 offset:2048
	ds_read_b128 v[186:189], v249 offset:3072
	v_mfma_f32_16x16x32_bf16 v[50:53], v[230:233], v[190:193], v[50:53]
	ds_read_b128 v[190:193], v169
	v_mfma_f32_16x16x32_bf16 v[50:53], v[234:237], v[194:197], v[50:53]
	ds_read_b128 v[194:197], v169 offset:1024
	v_mfma_f32_16x16x32_bf16 v[38:41], v[222:225], v[198:201], v[38:41]
	v_mfma_f32_16x16x32_bf16 v[38:41], v[226:229], v[202:205], v[38:41]
	v_mfma_f32_16x16x32_bf16 v[34:37], v[230:233], v[198:201], v[34:37]
	ds_read_b128 v[198:201], v169 offset:2048
	v_mfma_f32_16x16x32_bf16 v[34:37], v[234:237], v[202:205], v[34:37]
	ds_read_b128 v[202:205], v169 offset:3072
	v_mfma_f32_16x16x32_bf16 v[22:25], v[222:225], v[206:209], v[22:25]
	v_mfma_f32_16x16x32_bf16 v[22:25], v[226:229], v[210:213], v[22:25]
	v_mfma_f32_16x16x32_bf16 v[18:21], v[230:233], v[206:209], v[18:21]
	ds_read_b128 v[206:209], v169 offset:4096
	v_mfma_f32_16x16x32_bf16 v[18:21], v[234:237], v[210:213], v[18:21]
	ds_read_b128 v[210:213], v169 offset:5120
	v_mfma_f32_16x16x32_bf16 v[6:9], v[222:225], v[214:217], v[6:9]
	v_mfma_f32_16x16x32_bf16 v[6:9], v[226:229], v[218:221], v[6:9]
	v_mfma_f32_16x16x32_bf16 v[2:5], v[230:233], v[214:217], v[2:5]
	s_barrier
	v_mfma_f32_16x16x32_bf16 v[2:5], v[234:237], v[218:221], v[2:5]
	s_setprio 0
	s_add_i32 s50, s50, 2
	s_add_u32 vcc_lo, vcc_lo, 0x100
	s_addc_u32 s35, s35, 0
	s_add_u32 s38, s38, 0x100
	s_addc_u32 s39, s39, 0
	s_cmp_gt_u32 s50, 13
	s_cbranch_scc0 .LBB0_165
	s_waitcnt lgkmcnt(0)
	s_and_b64 vcc, exec, s[40:41]
	s_cbranch_vccz .LBB0_168
	s_barrier

; #define PG8_STAGE(bufoff, gbase, voff) do { _Pragma("unroll") for (int _i = 0; _i < 2; ++_i) \
;         __builtin_amdgcn_global_load_lds((const unsigned*)((const char*)(gbase) + (voff)[_i]), (LAS unsigned*)(lds + (bufoff) + ldsw + _i * 8192), 16, 0, 0); } while (0)
; #define PG8_LDA(dst, b, h) do { _Pragma("unroll") for (int m = 0; m < 4; ++m) _Pragma("unroll") for (int k = 0; k < 2; ++k) dst[m][k] = *(const LAS bf16x8*)(lds + PG8_SA(b, h) + aoff + m * 2048 + k * 1024); } while (0)
; #define PG8_LDB(dst, b, h) do { _Pragma("unroll") for (int n = 0; n < 2; ++n) _Pragma("unroll") for (int k = 0; k < 2; ++k) dst[n][k] = *(const LAS bf16x8*)(lds + PG8_SB(b, h) + boff + n * 2048 + k * 1024); } while (0)
; #define PG8_MMA(ai, bj, At, Bt) do { __builtin_amdgcn_s_setprio(1); _Pragma("unroll") for (int m = 0; m < 4; ++m) _Pragma("unroll") for (int n = 0; n < 2; ++n) _Pragma("unroll") for (int k = 0; k < 2; ++k) \
;         acc[ai][bj][m][n] = __builtin_amdgcn_mfma_f32_16x16x32_bf16(Bt[n][k], At[m][k], acc[ai][bj][m][n], 0, 0, 0); __builtin_amdgcn_s_setprio(0); } while (0)
; #define PG8_WAIT_V(n) asm volatile("s_waitcnt vmcnt(" #n ")" ::: "memory")
; #define PG8_WAIT_L(n) asm volatile("s_waitcnt lgkmcnt(" #n ")" ::: "memory")
; #define PG8_BAR __builtin_amdgcn_s_barrier()
; template <class Epi, class Sched>
; __device__ __forceinline__ void gemm_phase(LAS unsigned char* lds, const Gemm g, const Sched& S, const Epi& E) {
;     ...
;             const bool last = (t == nt - 2);
;             const char* a1 = cA + (size_t)(t + 1) * kstep;
;             const char* a2 = last ? nA : cA + (size_t)(t + 2) * kstep; const char* b2 = last ? nB : cB + (size_t)(t + 2) * kstep;
;             const char* a3 = a2 + kstep; const char* b3 = b2 + kstep;
;             PG8_LDB(B0, 0, 0); PG8_SCHED; PG8_LDA(At, 0, 0); PG8_STAGE(PG8_SA(1, 1), a1 + hstep, voffA);
;             PG8_WAIT_L(8); PG8_BAR; PG8_WAIT_L(0); PG8_MMA(0, 0, At, B0); PG8_BAR; PG8_SCHED;
;             PG8_LDB(B1, 0, 1); PG8_STAGE(PG8_SB(0, 0), b2, voffB);
;             PG8_BAR; PG8_WAIT_L(0); PG8_MMA(0, 1, At, B1); PG8_BAR;
;             PG8_LDA(At, 0, 1); PG8_STAGE(PG8_SA(0, 0), a2, voffA);
;             PG8_BAR; PG8_WAIT_L(0); PG8_MMA(1, 0, At, B0); PG8_BAR; PG8_SCHED;
;             PG8_STAGE(PG8_SB(0, 1), b2 + hstep, voffB);
;             PG8_WAIT_V(6); PG8_BAR; PG8_MMA(1, 1, At, B1); PG8_BAR;
.LBB0_416:
	s_add_u32 s24, s0, 0xfffc0080
	s_addc_u32 s25, s1, -1
	s_add_i32 s39, 0, 0x10000
	v_add_u32_e32 v142, s39, v144
	s_cmp_eq_u32 s38, 12
	s_cselect_b32 vcc_hi, s77, s25
	s_cselect_b32 vcc_lo, s76, s24
	s_cselect_b32 s37, s47, s50
	s_cselect_b32 s36, s61, s35
	s_add_i32 m0, s93, 0xc000
	ds_read_b128 v[218:221], v162 offset:6144
	ds_read_b128 v[222:225], v162 offset:7168
	global_load_lds_dwordx4 v140, s[0:1]
	s_add_i32 m0, s93, 0xe000
	s_nop 0
	global_load_lds_dwordx4 v138, s[0:1]
	s_waitcnt lgkmcnt(8)
	s_barrier
	s_waitcnt lgkmcnt(0)
	s_setprio 1
	s_waitcnt lgkmcnt(0)
	v_mfma_f32_16x16x32_bf16 v[126:129], v[164:167], v[194:197], v[126:129]
	v_mfma_f32_16x16x32_bf16 v[126:129], v[182:185], v[198:201], v[126:129]
	v_mfma_f32_16x16x32_bf16 v[122:125], v[186:189], v[194:197], v[122:125]
	v_mfma_f32_16x16x32_bf16 v[122:125], v[190:193], v[198:201], v[122:125]
	v_mfma_f32_16x16x32_bf16 v[118:121], v[164:167], v[202:205], v[118:121]
	v_mfma_f32_16x16x32_bf16 v[118:121], v[182:185], v[206:209], v[118:121]
	v_mfma_f32_16x16x32_bf16 v[110:113], v[186:189], v[202:205], v[110:113]
	v_mfma_f32_16x16x32_bf16 v[110:113], v[190:193], v[206:209], v[110:113]
	v_mfma_f32_16x16x32_bf16 v[102:105], v[164:167], v[210:213], v[102:105]
	v_mfma_f32_16x16x32_bf16 v[102:105], v[182:185], v[214:217], v[102:105]
	v_mfma_f32_16x16x32_bf16 v[94:97], v[186:189], v[210:213], v[94:97]
	v_mfma_f32_16x16x32_bf16 v[94:97], v[190:193], v[214:217], v[94:97]
	v_mfma_f32_16x16x32_bf16 v[86:89], v[164:167], v[218:221], v[86:89]
	v_mfma_f32_16x16x32_bf16 v[86:89], v[182:185], v[222:225], v[86:89]
	v_mfma_f32_16x16x32_bf16 v[78:81], v[186:189], v[218:221], v[78:81]
	s_barrier
	v_mfma_f32_16x16x32_bf16 v[78:81], v[190:193], v[222:225], v[78:81]
	s_setprio 0
	s_add_i32 s51, 0, 0x14000
	v_add_u32_e32 v142, s51, v144
	s_add_i32 s24, s39, s86
	ds_read_b128 v[226:229], v142
	ds_read_b128 v[230:233], v142 offset:1024
	ds_read_b128 v[234:237], v142 offset:2048
	ds_read_b128 v[238:241], v142 offset:3072
	s_mov_b32 m0, s24
	global_load_lds_dwordx4 v134, s[36:37]
	s_add_i32 m0, s24, 0x2000
	s_nop 0
	global_load_lds_dwordx4 v130, s[36:37]
	s_barrier
	s_waitcnt lgkmcnt(0)
	s_setprio 1
	s_waitcnt lgkmcnt(0)
	v_mfma_f32_16x16x32_bf16 v[114:117], v[226:229], v[194:197], v[114:117]
	v_mfma_f32_16x16x32_bf16 v[114:117], v[230:233], v[198:201], v[114:117]
	v_mfma_f32_16x16x32_bf16 v[106:109], v[234:237], v[194:197], v[106:109]
	v_mfma_f32_16x16x32_bf16 v[106:109], v[238:241], v[198:201], v[106:109]
	v_mfma_f32_16x16x32_bf16 v[98:101], v[226:229], v[202:205], v[98:101]
	v_mfma_f32_16x16x32_bf16 v[98:101], v[230:233], v[206:209], v[98:101]
	v_mfma_f32_16x16x32_bf16 v[90:93], v[234:237], v[202:205], v[90:93]
	v_mfma_f32_16x16x32_bf16 v[90:93], v[238:241], v[206:209], v[90:93]
	v_mfma_f32_16x16x32_bf16 v[82:85], v[226:229], v[210:213], v[82:85]
	v_mfma_f32_16x16x32_bf16 v[82:85], v[230:233], v[214:217], v[82:85]
	v_mfma_f32_16x16x32_bf16 v[74:77], v[234:237], v[210:213], v[74:77]
	v_mfma_f32_16x16x32_bf16 v[74:77], v[238:241], v[214:217], v[74:77]
	v_mfma_f32_16x16x32_bf16 v[70:73], v[226:229], v[218:221], v[70:73]
	v_mfma_f32_16x16x32_bf16 v[70:73], v[230:233], v[222:225], v[70:73]
	v_mfma_f32_16x16x32_bf16 v[66:69], v[234:237], v[218:221], v[66:69]
	s_barrier
	v_mfma_f32_16x16x32_bf16 v[66:69], v[238:241], v[222:225], v[66:69]
	s_setprio 0
	s_mov_b32 m0, s93
	ds_read_b128 v[194:197], v162 offset:16384
	ds_read_b128 v[198:201], v162 offset:17408
	ds_read_b128 v[202:205], v162 offset:18432
	ds_read_b128 v[206:209], v162 offset:19456
	ds_read_b128 v[210:213], v162 offset:20480
	ds_read_b128 v[214:217], v162 offset:21504
	ds_read_b128 v[218:221], v162 offset:22528
	ds_read_b128 v[222:225], v162 offset:23552
	global_load_lds_dwordx4 v136, vcc
	s_mov_b32 m0, s94
	s_nop 0
	global_load_lds_dwordx4 v132, vcc
	s_waitcnt vmcnt(8)
	s_barrier
	s_waitcnt lgkmcnt(0)
	s_setprio 1
	s_waitcnt lgkmcnt(0)
	v_mfma_f32_16x16x32_bf16 v[62:65], v[164:167], v[194:197], v[62:65]
	v_mfma_f32_16x16x32_bf16 v[62:65], v[182:185], v[198:201], v[62:65]
	v_mfma_f32_16x16x32_bf16 v[58:61], v[186:189], v[194:197], v[58:61]
	v_mfma_f32_16x16x32_bf16 v[58:61], v[190:193], v[198:201], v[58:61]
	v_mfma_f32_16x16x32_bf16 v[54:57], v[164:167], v[202:205], v[54:57]
	v_mfma_f32_16x16x32_bf16 v[54:57], v[182:185], v[206:209], v[54:57]
	v_mfma_f32_16x16x32_bf16 v[46:49], v[186:189], v[202:205], v[46:49]
	v_mfma_f32_16x16x32_bf16 v[46:49], v[190:193], v[206:209], v[46:49]
	v_mfma_f32_16x16x32_bf16 v[38:41], v[164:167], v[210:213], v[38:41]
	v_mfma_f32_16x16x32_bf16 v[38:41], v[182:185], v[214:217], v[38:41]
	v_mfma_f32_16x16x32_bf16 v[30:33], v[186:189], v[210:213], v[30:33]
	v_mfma_f32_16x16x32_bf16 v[30:33], v[190:193], v[214:217], v[30:33]
	v_mfma_f32_16x16x32_bf16 v[22:25], v[164:167], v[218:221], v[22:25]
	v_mfma_f32_16x16x32_bf16 v[22:25], v[182:185], v[222:225], v[22:25]
	v_mfma_f32_16x16x32_bf16 v[14:17], v[186:189], v[218:221], v[14:17]
	s_barrier
	v_mfma_f32_16x16x32_bf16 v[14:17], v[190:193], v[222:225], v[14:17]
	s_setprio 0
	s_add_u32 s24, s36, 0x40000
	s_addc_u32 s25, s37, 0
	s_add_i32 s39, s51, s86
	s_mov_b32 m0, s39
	s_nop 0
	global_load_lds_dwordx4 v134, s[24:25]
	s_add_i32 m0, s39, 0x2000
	s_nop 0
	global_load_lds_dwordx4 v130, s[24:25]
	s_waitcnt vmcnt(6)
	s_barrier
; #define PG8_STAGE(bufoff, gbase, voff) do { _Pragma("unroll") for (int _i = 0; _i < 2; ++_i) \
;         __builtin_amdgcn_global_load_lds((const unsigned*)((const char*)(gbase) + (voff)[_i]), (LAS unsigned*)(lds + (bufoff) + ldsw + _i * 8192), 16, 0, 0); } while (0)
; #define PG8_LDA(dst, b, h) do { _Pragma("unroll") for (int m = 0; m < 4; ++m) _Pragma("unroll") for (int k = 0; k < 2; ++k) dst[m][k] = *(const LAS bf16x8*)(lds + PG8_SA(b, h) + aoff + m * 2048 + k * 1024); } while (0)
; #define PG8_LDB(dst, b, h) do { _Pragma("unroll") for (int n = 0; n < 2; ++n) _Pragma("unroll") for (int k = 0; k < 2; ++k) dst[n][k] = *(const LAS bf16x8*)(lds + PG8_SB(b, h) + boff + n * 2048 + k * 1024); } while (0)
; #define PG8_MMA(ai, bj, At, Bt) do { __builtin_amdgcn_s_setprio(1); _Pragma("unroll") for (int m = 0; m < 4; ++m) _Pragma("unroll") for (int n = 0; n < 2; ++n) _Pragma("unroll") for (int k = 0; k < 2; ++k) \
;         acc[ai][bj][m][n] = __builtin_amdgcn_mfma_f32_16x16x32_bf16(Bt[n][k], At[m][k], acc[ai][bj][m][n], 0, 0, 0); __builtin_amdgcn_s_setprio(0); } while (0)
; #define PG8_WAIT_V(n) asm volatile("s_waitcnt vmcnt(" #n ")" ::: "memory")
; #define PG8_WAIT_L(n) asm volatile("s_waitcnt lgkmcnt(" #n ")" ::: "memory")
; #define PG8_BAR __builtin_amdgcn_s_barrier()
; #define PG8_SCHED __builtin_amdgcn_sched_barrier(0)
; template <class Epi, class Sched>
; __device__ __forceinline__ void gemm_phase(LAS unsigned char* lds, const Gemm g, const Sched& S, const Epi& E) {
;     ...
;             PG8_WAIT_V(6); PG8_BAR; PG8_MMA(1, 1, At, B1); PG8_BAR;
;             PG8_LDB(B0, 1, 0); PG8_SCHED; PG8_LDA(At, 1, 0); PG8_STAGE(PG8_SA(0, 1), a2 + hstep, voffA);
;             PG8_WAIT_L(8); PG8_BAR; PG8_WAIT_L(0); PG8_MMA(0, 0, At, B0); PG8_BAR; PG8_SCHED;
;             PG8_LDB(B1, 1, 1); PG8_STAGE(PG8_SB(1, 0), b3, voffB);
;             PG8_BAR; PG8_WAIT_L(0); PG8_MMA(0, 1, At, B1); PG8_BAR;
	s_setprio 1
	v_add_u32_e32 v249, 0x18000, v144
	v_mfma_f32_16x16x32_bf16 v[50:53], v[226:229], v[194:197], v[50:53]
	ds_read_b128 v[164:167], v249
	ds_read_b128 v[182:185], v249 offset:1024
	v_mfma_f32_16x16x32_bf16 v[50:53], v[230:233], v[198:201], v[50:53]
	ds_read_b128 v[186:189], v249 offset:2048
	ds_read_b128 v[190:193], v249 offset:3072
	v_mfma_f32_16x16x32_bf16 v[42:45], v[234:237], v[194:197], v[42:45]
	ds_read_b128 v[194:197], v162 offset:32768
	v_mfma_f32_16x16x32_bf16 v[42:45], v[238:241], v[198:201], v[42:45]
	ds_read_b128 v[198:201], v162 offset:33792
	v_mfma_f32_16x16x32_bf16 v[34:37], v[226:229], v[202:205], v[34:37]
	v_mfma_f32_16x16x32_bf16 v[34:37], v[230:233], v[206:209], v[34:37]
	v_mfma_f32_16x16x32_bf16 v[26:29], v[234:237], v[202:205], v[26:29]
	ds_read_b128 v[202:205], v162 offset:34816
	v_mfma_f32_16x16x32_bf16 v[26:29], v[238:241], v[206:209], v[26:29]
	ds_read_b128 v[206:209], v162 offset:35840
	v_mfma_f32_16x16x32_bf16 v[18:21], v[226:229], v[210:213], v[18:21]
	v_mfma_f32_16x16x32_bf16 v[18:21], v[230:233], v[214:217], v[18:21]
	v_mfma_f32_16x16x32_bf16 v[10:13], v[234:237], v[210:213], v[10:13]
	ds_read_b128 v[210:213], v162 offset:36864
	v_mfma_f32_16x16x32_bf16 v[10:13], v[238:241], v[214:217], v[10:13]
	ds_read_b128 v[214:217], v162 offset:37888
	v_mfma_f32_16x16x32_bf16 v[6:9], v[226:229], v[218:221], v[6:9]
	v_mfma_f32_16x16x32_bf16 v[6:9], v[230:233], v[222:225], v[6:9]
	v_mfma_f32_16x16x32_bf16 v[2:5], v[234:237], v[218:221], v[2:5]
	s_barrier
	v_mfma_f32_16x16x32_bf16 v[2:5], v[238:241], v[222:225], v[2:5]
	s_setprio 0
	s_add_i32 s39, 0, 0x18000
	v_add_u32_e32 v163, s39, v144
	s_add_u32 s24, vcc_lo, 0x40000
	s_addc_u32 s25, vcc_hi, 0
	s_mov_b32 m0, s95
	ds_read_b128 v[218:221], v162 offset:38912
	ds_read_b128 v[222:225], v162 offset:39936
	global_load_lds_dwordx4 v136, s[24:25]
	s_mov_b32 m0, s96
	s_nop 0
	global_load_lds_dwordx4 v132, s[24:25]
	s_waitcnt lgkmcnt(8)
	s_barrier
	s_waitcnt lgkmcnt(0)
	s_setprio 1
	s_waitcnt lgkmcnt(0)
	v_mfma_f32_16x16x32_bf16 v[126:129], v[164:167], v[194:197], v[126:129]
	v_mfma_f32_16x16x32_bf16 v[126:129], v[182:185], v[198:201], v[126:129]
	v_mfma_f32_16x16x32_bf16 v[122:125], v[186:189], v[194:197], v[122:125]
	v_mfma_f32_16x16x32_bf16 v[122:125], v[190:193], v[198:201], v[122:125]
	v_mfma_f32_16x16x32_bf16 v[118:121], v[164:167], v[202:205], v[118:121]
	v_mfma_f32_16x16x32_bf16 v[118:121], v[182:185], v[206:209], v[118:121]
	v_mfma_f32_16x16x32_bf16 v[110:113], v[186:189], v[202:205], v[110:113]
	v_mfma_f32_16x16x32_bf16 v[110:113], v[190:193], v[206:209], v[110:113]
	v_mfma_f32_16x16x32_bf16 v[102:105], v[164:167], v[210:213], v[102:105]
	v_mfma_f32_16x16x32_bf16 v[102:105], v[182:185], v[214:217], v[102:105]
	v_mfma_f32_16x16x32_bf16 v[94:97], v[186:189], v[210:213], v[94:97]
	v_mfma_f32_16x16x32_bf16 v[94:97], v[190:193], v[214:217], v[94:97]
	v_mfma_f32_16x16x32_bf16 v[86:89], v[164:167], v[218:221], v[86:89]
	v_mfma_f32_16x16x32_bf16 v[86:89], v[182:185], v[222:225], v[86:89]
	v_mfma_f32_16x16x32_bf16 v[78:81], v[186:189], v[218:221], v[78:81]
	s_barrier
	v_mfma_f32_16x16x32_bf16 v[78:81], v[190:193], v[222:225], v[78:81]
	s_setprio 0
	s_add_i32 s51, 0, 0x1c000
	s_add_i32 s24, s39, s86
	v_add_u32_e32 v163, s51, v144
	s_add_i32 m0, s24, 0xffffff80
	ds_read_b128 v[226:229], v163
	ds_read_b128 v[230:233], v163 offset:1024
	ds_read_b128 v[234:237], v163 offset:2048
	ds_read_b128 v[238:241], v163 offset:3072
	global_load_lds_dwordx4 v134, s[36:37] offset:128
	s_add_i32 m0, s24, 0x1f80
	s_nop 0
	global_load_lds_dwordx4 v130, s[36:37] offset:128
	s_barrier
	s_waitcnt lgkmcnt(0)
	s_setprio 1
	s_waitcnt lgkmcnt(0)
	v_mfma_f32_16x16x32_bf16 v[114:117], v[226:229], v[194:197], v[114:117]
	v_mfma_f32_16x16x32_bf16 v[114:117], v[230:233], v[198:201], v[114:117]
	v_mfma_f32_16x16x32_bf16 v[106:109], v[234:237], v[194:197], v[106:109]
	v_mfma_f32_16x16x32_bf16 v[106:109], v[238:241], v[198:201], v[106:109]
	v_mfma_f32_16x16x32_bf16 v[98:101], v[226:229], v[202:205], v[98:101]
	v_mfma_f32_16x16x32_bf16 v[98:101], v[230:233], v[206:209], v[98:101]
	v_mfma_f32_16x16x32_bf16 v[90:93], v[234:237], v[202:205], v[90:93]
	v_mfma_f32_16x16x32_bf16 v[90:93], v[238:241], v[206:209], v[90:93]
	v_mfma_f32_16x16x32_bf16 v[82:85], v[226:229], v[210:213], v[82:85]
	v_mfma_f32_16x16x32_bf16 v[82:85], v[230:233], v[214:217], v[82:85]
	v_mfma_f32_16x16x32_bf16 v[74:77], v[234:237], v[210:213], v[74:77]
	v_mfma_f32_16x16x32_bf16 v[74:77], v[238:241], v[214:217], v[74:77]
	v_mfma_f32_16x16x32_bf16 v[70:73], v[226:229], v[218:221], v[70:73]
	v_mfma_f32_16x16x32_bf16 v[70:73], v[230:233], v[222:225], v[70:73]
	v_mfma_f32_16x16x32_bf16 v[66:69], v[234:237], v[218:221], v[66:69]
	s_barrier
; #define PG8_STAGE(bufoff, gbase, voff) do { _Pragma("unroll") for (int _i = 0; _i < 2; ++_i) \
;         __builtin_amdgcn_global_load_lds((const unsigned*)((const char*)(gbase) + (voff)[_i]), (LAS unsigned*)(lds + (bufoff) + ldsw + _i * 8192), 16, 0, 0); } while (0)
; #define PG8_LDA(dst, b, h) do { _Pragma("unroll") for (int m = 0; m < 4; ++m) _Pragma("unroll") for (int k = 0; k < 2; ++k) dst[m][k] = *(const LAS bf16x8*)(lds + PG8_SA(b, h) + aoff + m * 2048 + k * 1024); } while (0)
; #define PG8_MMA(ai, bj, At, Bt) do { __builtin_amdgcn_s_setprio(1); _Pragma("unroll") for (int m = 0; m < 4; ++m) _Pragma("unroll") for (int n = 0; n < 2; ++n) _Pragma("unroll") for (int k = 0; k < 2; ++k) \
;         acc[ai][bj][m][n] = __builtin_amdgcn_mfma_f32_16x16x32_bf16(Bt[n][k], At[m][k], acc[ai][bj][m][n], 0, 0, 0); __builtin_amdgcn_s_setprio(0); } while (0)
; #define PG8_WAIT_V(n) asm volatile("s_waitcnt vmcnt(" #n ")" ::: "memory")
; #define PG8_WAIT_L(n) asm volatile("s_waitcnt lgkmcnt(" #n ")" ::: "memory")
; #define PG8_BAR __builtin_amdgcn_s_barrier()
; #define PG8_SCHED __builtin_amdgcn_sched_barrier(0)
; template <class Epi, class Sched>
; __device__ __forceinline__ void gemm_phase(LAS unsigned char* lds, const Gemm g, const Sched& S, const Epi& E) {
;     ...
;             PG8_LDA(At, 1, 1); PG8_STAGE(PG8_SA(1, 0), a3, voffA);
;             PG8_BAR; PG8_WAIT_L(0); PG8_MMA(1, 0, At, B0); PG8_BAR; PG8_SCHED;
;             PG8_STAGE(PG8_SB(1, 1), b3 + hstep, voffB);
;             PG8_WAIT_V(6); PG8_BAR; PG8_MMA(1, 1, At, B1); PG8_BAR;
;         }
	v_mfma_f32_16x16x32_bf16 v[66:69], v[238:241], v[222:225], v[66:69]
	s_setprio 0
	s_add_i32 m0, s97, 0xffffff80
	ds_read_b128 v[194:197], v162 offset:49152
	ds_read_b128 v[198:201], v162 offset:50176
	ds_read_b128 v[202:205], v162 offset:51200
	ds_read_b128 v[206:209], v162 offset:52224
	ds_read_b128 v[210:213], v162 offset:53248
	ds_read_b128 v[214:217], v162 offset:54272
	ds_read_b128 v[218:221], v162 offset:55296
	ds_read_b128 v[222:225], v162 offset:56320
	global_load_lds_dwordx4 v136, vcc offset:128
	s_add_i32 m0, s98, 0xffffff80
	s_nop 0
	global_load_lds_dwordx4 v132, vcc offset:128
	s_waitcnt vmcnt(8)
	s_barrier
	s_waitcnt lgkmcnt(0)
	s_setprio 1
	s_waitcnt lgkmcnt(0)
	v_mfma_f32_16x16x32_bf16 v[62:65], v[164:167], v[194:197], v[62:65]
	v_mfma_f32_16x16x32_bf16 v[62:65], v[182:185], v[198:201], v[62:65]
	v_mfma_f32_16x16x32_bf16 v[58:61], v[186:189], v[194:197], v[58:61]
	v_mfma_f32_16x16x32_bf16 v[58:61], v[190:193], v[198:201], v[58:61]
	v_mfma_f32_16x16x32_bf16 v[54:57], v[164:167], v[202:205], v[54:57]
	v_mfma_f32_16x16x32_bf16 v[54:57], v[182:185], v[206:209], v[54:57]
	v_mfma_f32_16x16x32_bf16 v[46:49], v[186:189], v[202:205], v[46:49]
	v_mfma_f32_16x16x32_bf16 v[46:49], v[190:193], v[206:209], v[46:49]
	v_mfma_f32_16x16x32_bf16 v[38:41], v[164:167], v[210:213], v[38:41]
	v_mfma_f32_16x16x32_bf16 v[38:41], v[182:185], v[214:217], v[38:41]
	v_mfma_f32_16x16x32_bf16 v[30:33], v[186:189], v[210:213], v[30:33]
	v_mfma_f32_16x16x32_bf16 v[30:33], v[190:193], v[214:217], v[30:33]
	v_mfma_f32_16x16x32_bf16 v[22:25], v[164:167], v[218:221], v[22:25]
	v_mfma_f32_16x16x32_bf16 v[22:25], v[182:185], v[222:225], v[22:25]
	v_mfma_f32_16x16x32_bf16 v[14:17], v[186:189], v[218:221], v[14:17]
	s_barrier
	v_mfma_f32_16x16x32_bf16 v[14:17], v[190:193], v[222:225], v[14:17]
	s_setprio 0
	s_add_u32 s24, s36, 0x40080
	s_addc_u32 s25, s37, 0
	s_add_i32 s36, s51, s86
	s_mov_b32 m0, s36
	s_nop 0
	global_load_lds_dwordx4 v134, s[24:25]
	s_add_i32 m0, s36, 0x2000
	s_nop 0
	global_load_lds_dwordx4 v130, s[24:25]
	s_waitcnt vmcnt(6)
	s_barrier
	s_setprio 1
	v_add_u32_e32 v249, 0x10000, v144
	v_mfma_f32_16x16x32_bf16 v[50:53], v[226:229], v[194:197], v[50:53]
	ds_read_b128 v[164:167], v249
	ds_read_b128 v[182:185], v249 offset:1024
	v_mfma_f32_16x16x32_bf16 v[50:53], v[230:233], v[198:201], v[50:53]
	ds_read_b128 v[186:189], v249 offset:2048
	ds_read_b128 v[190:193], v249 offset:3072
	v_mfma_f32_16x16x32_bf16 v[42:45], v[234:237], v[194:197], v[42:45]
	ds_read_b128 v[194:197], v162
	v_mfma_f32_16x16x32_bf16 v[42:45], v[238:241], v[198:201], v[42:45]
	ds_read_b128 v[198:201], v162 offset:1024
	v_mfma_f32_16x16x32_bf16 v[34:37], v[226:229], v[202:205], v[34:37]
	v_mfma_f32_16x16x32_bf16 v[34:37], v[230:233], v[206:209], v[34:37]
	v_mfma_f32_16x16x32_bf16 v[26:29], v[234:237], v[202:205], v[26:29]
	ds_read_b128 v[202:205], v162 offset:2048
	v_mfma_f32_16x16x32_bf16 v[26:29], v[238:241], v[206:209], v[26:29]
	ds_read_b128 v[206:209], v162 offset:3072
	v_mfma_f32_16x16x32_bf16 v[18:21], v[226:229], v[210:213], v[18:21]
	v_mfma_f32_16x16x32_bf16 v[18:21], v[230:233], v[214:217], v[18:21]
	v_mfma_f32_16x16x32_bf16 v[10:13], v[234:237], v[210:213], v[10:13]
	ds_read_b128 v[210:213], v162 offset:4096
	v_mfma_f32_16x16x32_bf16 v[10:13], v[238:241], v[214:217], v[10:13]
	ds_read_b128 v[214:217], v162 offset:5120
	v_mfma_f32_16x16x32_bf16 v[6:9], v[226:229], v[218:221], v[6:9]
	v_mfma_f32_16x16x32_bf16 v[6:9], v[230:233], v[222:225], v[6:9]
	v_mfma_f32_16x16x32_bf16 v[2:5], v[234:237], v[218:221], v[2:5]
	s_barrier
	v_mfma_f32_16x16x32_bf16 v[2:5], v[238:241], v[222:225], v[2:5]
	s_setprio 0
	s_add_i32 s38, s38, 2
	s_add_u32 s35, s35, 0x100
	s_addc_u32 s50, s50, 0
	s_add_u32 s0, s0, 0x100
	s_addc_u32 s1, s1, 0
	s_cmp_gt_u32 s38, 13
	s_cbranch_scc0 .LBB0_416
	s_waitcnt lgkmcnt(0)
	s_and_b64 vcc, exec, s[44:45]
	s_cbranch_vccz .LBB0_419
	s_barrier

; #define PG8_STAGE(bufoff, gbase, voff) do { _Pragma("unroll") for (int _i = 0; _i < 2; ++_i) \
;         __builtin_amdgcn_global_load_lds((const unsigned*)((const char*)(gbase) + (voff)[_i]), (LAS unsigned*)(lds + (bufoff) + ldsw + _i * 8192), 16, 0, 0); } while (0)
; #define PG8_LDA(dst, b, h) do { _Pragma("unroll") for (int m = 0; m < 4; ++m) _Pragma("unroll") for (int k = 0; k < 2; ++k) dst[m][k] = *(const LAS bf16x8*)(lds + PG8_SA(b, h) + aoff + m * 2048 + k * 1024); } while (0)
; #define PG8_LDB(dst, b, h) do { _Pragma("unroll") for (int n = 0; n < 2; ++n) _Pragma("unroll") for (int k = 0; k < 2; ++k) dst[n][k] = *(const LAS bf16x8*)(lds + PG8_SB(b, h) + boff + n * 2048 + k * 1024); } while (0)
; #define PG8_MMA(ai, bj, At, Bt) do { __builtin_amdgcn_s_setprio(1); _Pragma("unroll") for (int m = 0; m < 4; ++m) _Pragma("unroll") for (int n = 0; n < 2; ++n) _Pragma("unroll") for (int k = 0; k < 2; ++k) \
;         acc[ai][bj][m][n] = __builtin_amdgcn_mfma_f32_16x16x32_bf16(Bt[n][k], At[m][k], acc[ai][bj][m][n], 0, 0, 0); __builtin_amdgcn_s_setprio(0); } while (0)
; #define PG8_WAIT_V(n) asm volatile("s_waitcnt vmcnt(" #n ")" ::: "memory")
; #define PG8_WAIT_L(n) asm volatile("s_waitcnt lgkmcnt(" #n ")" ::: "memory")
; #define PG8_BAR __builtin_amdgcn_s_barrier()
; template <class Epi, class Sched>
; __device__ __forceinline__ void gemm_phase(LAS unsigned char* lds, const Gemm g, const Sched& S, const Epi& E) {
;     ...
;             const bool last = (t == nt - 2);
;             const char* a1 = cA + (size_t)(t + 1) * kstep;
;             const char* a2 = last ? nA : cA + (size_t)(t + 2) * kstep; const char* b2 = last ? nB : cB + (size_t)(t + 2) * kstep;
;             const char* a3 = a2 + kstep; const char* b3 = b2 + kstep;
;             PG8_LDB(B0, 0, 0); PG8_SCHED; PG8_LDA(At, 0, 0); PG8_STAGE(PG8_SA(1, 1), a1 + hstep, voffA);
;             PG8_WAIT_L(8); PG8_BAR; PG8_WAIT_L(0); PG8_MMA(0, 0, At, B0); PG8_BAR; PG8_SCHED;
;             PG8_LDB(B1, 0, 1); PG8_STAGE(PG8_SB(0, 0), b2, voffB);
;             PG8_BAR; PG8_WAIT_L(0); PG8_MMA(0, 1, At, B1); PG8_BAR;
;             PG8_LDA(At, 0, 1); PG8_STAGE(PG8_SA(0, 0), a2, voffA);
;             PG8_BAR; PG8_WAIT_L(0); PG8_MMA(1, 0, At, B0); PG8_BAR; PG8_SCHED;
;             PG8_STAGE(PG8_SB(0, 1), b2 + hstep, voffB);
;             PG8_WAIT_V(6); PG8_BAR; PG8_MMA(1, 1, At, B1); PG8_BAR;
.LBB0_557:
	s_add_u32 s24, s0, 0xfffc0080
	s_addc_u32 s25, s1, -1
	s_add_i32 s39, 0, 0x10000
	v_add_u32_e32 v162, s39, v164
	s_cmp_eq_u32 s38, 12
	s_cselect_b32 vcc_hi, s77, s25
	s_cselect_b32 vcc_lo, s76, s24
	s_cselect_b32 s49, s45, s50
	s_cselect_b32 s48, s47, s35
	s_add_i32 m0, s95, 0xc000
	ds_read_b128 v[218:221], v166 offset:6144
	ds_read_b128 v[222:225], v166 offset:7168
	global_load_lds_dwordx4 v140, s[0:1]
	s_add_i32 m0, s95, 0xe000
	s_nop 0
	global_load_lds_dwordx4 v138, s[0:1]
	s_waitcnt lgkmcnt(8)
	s_barrier
	s_waitcnt lgkmcnt(0)
	s_setprio 1
	s_waitcnt lgkmcnt(0)
	v_mfma_f32_16x16x32_bf16 v[126:129], v[142:145], v[194:197], v[126:129]
	v_mfma_f32_16x16x32_bf16 v[126:129], v[182:185], v[198:201], v[126:129]
	v_mfma_f32_16x16x32_bf16 v[122:125], v[186:189], v[194:197], v[122:125]
	v_mfma_f32_16x16x32_bf16 v[122:125], v[190:193], v[198:201], v[122:125]
	v_mfma_f32_16x16x32_bf16 v[110:113], v[142:145], v[202:205], v[110:113]
	v_mfma_f32_16x16x32_bf16 v[110:113], v[182:185], v[206:209], v[110:113]
	v_mfma_f32_16x16x32_bf16 v[106:109], v[186:189], v[202:205], v[106:109]
	v_mfma_f32_16x16x32_bf16 v[106:109], v[190:193], v[206:209], v[106:109]
	v_mfma_f32_16x16x32_bf16 v[94:97], v[142:145], v[210:213], v[94:97]
	v_mfma_f32_16x16x32_bf16 v[94:97], v[182:185], v[214:217], v[94:97]
	v_mfma_f32_16x16x32_bf16 v[90:93], v[186:189], v[210:213], v[90:93]
	v_mfma_f32_16x16x32_bf16 v[90:93], v[190:193], v[214:217], v[90:93]
	v_mfma_f32_16x16x32_bf16 v[78:81], v[142:145], v[218:221], v[78:81]
	v_mfma_f32_16x16x32_bf16 v[78:81], v[182:185], v[222:225], v[78:81]
	v_mfma_f32_16x16x32_bf16 v[74:77], v[186:189], v[218:221], v[74:77]
	s_barrier
	v_mfma_f32_16x16x32_bf16 v[74:77], v[190:193], v[222:225], v[74:77]
	s_setprio 0
	s_add_i32 s51, 0, 0x14000
	v_add_u32_e32 v162, s51, v164
	s_add_i32 s24, s39, s94
	ds_read_b128 v[226:229], v162
	ds_read_b128 v[230:233], v162 offset:1024
	ds_read_b128 v[234:237], v162 offset:2048
	ds_read_b128 v[238:241], v162 offset:3072
	s_mov_b32 m0, s24
	global_load_lds_dwordx4 v134, s[48:49]
	s_add_i32 m0, s24, 0x2000
	s_nop 0
	global_load_lds_dwordx4 v130, s[48:49]
	s_barrier
	s_waitcnt lgkmcnt(0)
	s_setprio 1
	s_waitcnt lgkmcnt(0)
	v_mfma_f32_16x16x32_bf16 v[118:121], v[226:229], v[194:197], v[118:121]
	v_mfma_f32_16x16x32_bf16 v[118:121], v[230:233], v[198:201], v[118:121]
	v_mfma_f32_16x16x32_bf16 v[114:117], v[234:237], v[194:197], v[114:117]
	v_mfma_f32_16x16x32_bf16 v[114:117], v[238:241], v[198:201], v[114:117]
	v_mfma_f32_16x16x32_bf16 v[102:105], v[226:229], v[202:205], v[102:105]
	v_mfma_f32_16x16x32_bf16 v[102:105], v[230:233], v[206:209], v[102:105]
	v_mfma_f32_16x16x32_bf16 v[98:101], v[234:237], v[202:205], v[98:101]
	v_mfma_f32_16x16x32_bf16 v[98:101], v[238:241], v[206:209], v[98:101]
	v_mfma_f32_16x16x32_bf16 v[86:89], v[226:229], v[210:213], v[86:89]
	v_mfma_f32_16x16x32_bf16 v[86:89], v[230:233], v[214:217], v[86:89]
	v_mfma_f32_16x16x32_bf16 v[82:85], v[234:237], v[210:213], v[82:85]
	v_mfma_f32_16x16x32_bf16 v[82:85], v[238:241], v[214:217], v[82:85]
	v_mfma_f32_16x16x32_bf16 v[70:73], v[226:229], v[218:221], v[70:73]
	v_mfma_f32_16x16x32_bf16 v[70:73], v[230:233], v[222:225], v[70:73]
	v_mfma_f32_16x16x32_bf16 v[66:69], v[234:237], v[218:221], v[66:69]
	s_barrier
	v_mfma_f32_16x16x32_bf16 v[66:69], v[238:241], v[222:225], v[66:69]
	s_setprio 0
	s_mov_b32 m0, s95
	ds_read_b128 v[194:197], v166 offset:16384
	ds_read_b128 v[198:201], v166 offset:17408
	ds_read_b128 v[202:205], v166 offset:18432
	ds_read_b128 v[206:209], v166 offset:19456
	ds_read_b128 v[210:213], v166 offset:20480
	ds_read_b128 v[214:217], v166 offset:21504
	ds_read_b128 v[218:221], v166 offset:22528
	ds_read_b128 v[222:225], v166 offset:23552
	global_load_lds_dwordx4 v136, vcc
	s_mov_b32 m0, s96
	s_nop 0
	global_load_lds_dwordx4 v132, vcc
	s_waitcnt vmcnt(8)
	s_barrier
	s_waitcnt lgkmcnt(0)
	s_setprio 1
	s_waitcnt lgkmcnt(0)
	v_mfma_f32_16x16x32_bf16 v[62:65], v[142:145], v[194:197], v[62:65]
	v_mfma_f32_16x16x32_bf16 v[62:65], v[182:185], v[198:201], v[62:65]
	v_mfma_f32_16x16x32_bf16 v[58:61], v[186:189], v[194:197], v[58:61]
	v_mfma_f32_16x16x32_bf16 v[58:61], v[190:193], v[198:201], v[58:61]
	v_mfma_f32_16x16x32_bf16 v[46:49], v[142:145], v[202:205], v[46:49]
	v_mfma_f32_16x16x32_bf16 v[46:49], v[182:185], v[206:209], v[46:49]
	v_mfma_f32_16x16x32_bf16 v[42:45], v[186:189], v[202:205], v[42:45]
	v_mfma_f32_16x16x32_bf16 v[42:45], v[190:193], v[206:209], v[42:45]
	v_mfma_f32_16x16x32_bf16 v[30:33], v[142:145], v[210:213], v[30:33]
	v_mfma_f32_16x16x32_bf16 v[30:33], v[182:185], v[214:217], v[30:33]
	v_mfma_f32_16x16x32_bf16 v[26:29], v[186:189], v[210:213], v[26:29]
	v_mfma_f32_16x16x32_bf16 v[26:29], v[190:193], v[214:217], v[26:29]
	v_mfma_f32_16x16x32_bf16 v[14:17], v[142:145], v[218:221], v[14:17]
	v_mfma_f32_16x16x32_bf16 v[14:17], v[182:185], v[222:225], v[14:17]
	v_mfma_f32_16x16x32_bf16 v[10:13], v[186:189], v[218:221], v[10:13]
	s_barrier
	v_mfma_f32_16x16x32_bf16 v[10:13], v[190:193], v[222:225], v[10:13]
	s_setprio 0
	s_add_u32 s24, s48, 0x40000
	s_addc_u32 s25, s49, 0
	s_add_i32 s39, s51, s94
	s_mov_b32 m0, s39
	s_nop 0
	global_load_lds_dwordx4 v134, s[24:25]
	s_add_i32 m0, s39, 0x2000
	s_nop 0
	global_load_lds_dwordx4 v130, s[24:25]
	s_waitcnt vmcnt(6)
	s_barrier
; #define PG8_STAGE(bufoff, gbase, voff) do { _Pragma("unroll") for (int _i = 0; _i < 2; ++_i) \
;         __builtin_amdgcn_global_load_lds((const unsigned*)((const char*)(gbase) + (voff)[_i]), (LAS unsigned*)(lds + (bufoff) + ldsw + _i * 8192), 16, 0, 0); } while (0)
; #define PG8_LDA(dst, b, h) do { _Pragma("unroll") for (int m = 0; m < 4; ++m) _Pragma("unroll") for (int k = 0; k < 2; ++k) dst[m][k] = *(const LAS bf16x8*)(lds + PG8_SA(b, h) + aoff + m * 2048 + k * 1024); } while (0)
; #define PG8_LDB(dst, b, h) do { _Pragma("unroll") for (int n = 0; n < 2; ++n) _Pragma("unroll") for (int k = 0; k < 2; ++k) dst[n][k] = *(const LAS bf16x8*)(lds + PG8_SB(b, h) + boff + n * 2048 + k * 1024); } while (0)
; #define PG8_MMA(ai, bj, At, Bt) do { __builtin_amdgcn_s_setprio(1); _Pragma("unroll") for (int m = 0; m < 4; ++m) _Pragma("unroll") for (int n = 0; n < 2; ++n) _Pragma("unroll") for (int k = 0; k < 2; ++k) \
;         acc[ai][bj][m][n] = __builtin_amdgcn_mfma_f32_16x16x32_bf16(Bt[n][k], At[m][k], acc[ai][bj][m][n], 0, 0, 0); __builtin_amdgcn_s_setprio(0); } while (0)
; #define PG8_WAIT_V(n) asm volatile("s_waitcnt vmcnt(" #n ")" ::: "memory")
; #define PG8_WAIT_L(n) asm volatile("s_waitcnt lgkmcnt(" #n ")" ::: "memory")
; #define PG8_BAR __builtin_amdgcn_s_barrier()
; #define PG8_SCHED __builtin_amdgcn_sched_barrier(0)
; template <class Epi, class Sched>
; __device__ __forceinline__ void gemm_phase(LAS unsigned char* lds, const Gemm g, const Sched& S, const Epi& E) {
;     ...
;             PG8_WAIT_V(6); PG8_BAR; PG8_MMA(1, 1, At, B1); PG8_BAR;
;             PG8_LDB(B0, 1, 0); PG8_SCHED; PG8_LDA(At, 1, 0); PG8_STAGE(PG8_SA(0, 1), a2 + hstep, voffA);
;             PG8_WAIT_L(8); PG8_BAR; PG8_WAIT_L(0); PG8_MMA(0, 0, At, B0); PG8_BAR; PG8_SCHED;
;             PG8_LDB(B1, 1, 1); PG8_STAGE(PG8_SB(1, 0), b3, voffB);
;             PG8_BAR; PG8_WAIT_L(0); PG8_MMA(0, 1, At, B1); PG8_BAR;
	s_setprio 1
	v_add_u32_e32 v249, 0x18000, v164
	v_mfma_f32_16x16x32_bf16 v[54:57], v[226:229], v[194:197], v[54:57]
	ds_read_b128 v[142:145], v249
	ds_read_b128 v[182:185], v249 offset:1024
	v_mfma_f32_16x16x32_bf16 v[54:57], v[230:233], v[198:201], v[54:57]
	ds_read_b128 v[186:189], v249 offset:2048
	ds_read_b128 v[190:193], v249 offset:3072
	v_mfma_f32_16x16x32_bf16 v[50:53], v[234:237], v[194:197], v[50:53]
	ds_read_b128 v[194:197], v166 offset:32768
	v_mfma_f32_16x16x32_bf16 v[50:53], v[238:241], v[198:201], v[50:53]
	ds_read_b128 v[198:201], v166 offset:33792
	v_mfma_f32_16x16x32_bf16 v[38:41], v[226:229], v[202:205], v[38:41]
	v_mfma_f32_16x16x32_bf16 v[38:41], v[230:233], v[206:209], v[38:41]
	v_mfma_f32_16x16x32_bf16 v[34:37], v[234:237], v[202:205], v[34:37]
	ds_read_b128 v[202:205], v166 offset:34816
	v_mfma_f32_16x16x32_bf16 v[34:37], v[238:241], v[206:209], v[34:37]
	ds_read_b128 v[206:209], v166 offset:35840
	v_mfma_f32_16x16x32_bf16 v[22:25], v[226:229], v[210:213], v[22:25]
	v_mfma_f32_16x16x32_bf16 v[22:25], v[230:233], v[214:217], v[22:25]
	v_mfma_f32_16x16x32_bf16 v[18:21], v[234:237], v[210:213], v[18:21]
	ds_read_b128 v[210:213], v166 offset:36864
	v_mfma_f32_16x16x32_bf16 v[18:21], v[238:241], v[214:217], v[18:21]
	ds_read_b128 v[214:217], v166 offset:37888
	v_mfma_f32_16x16x32_bf16 v[6:9], v[226:229], v[218:221], v[6:9]
	v_mfma_f32_16x16x32_bf16 v[6:9], v[230:233], v[222:225], v[6:9]
	v_mfma_f32_16x16x32_bf16 v[2:5], v[234:237], v[218:221], v[2:5]
	s_barrier
	v_mfma_f32_16x16x32_bf16 v[2:5], v[238:241], v[222:225], v[2:5]
	s_setprio 0
	s_add_i32 s39, 0, 0x18000
	v_add_u32_e32 v167, s39, v164
	s_add_u32 s24, vcc_lo, 0x40000
	s_addc_u32 s25, vcc_hi, 0
	s_mov_b32 m0, s97
	ds_read_b128 v[218:221], v166 offset:38912
	ds_read_b128 v[222:225], v166 offset:39936
	global_load_lds_dwordx4 v136, s[24:25]
	s_mov_b32 m0, s98
	s_nop 0
	global_load_lds_dwordx4 v132, s[24:25]
	s_waitcnt lgkmcnt(8)
	s_barrier
	s_waitcnt lgkmcnt(0)
	s_setprio 1
	s_waitcnt lgkmcnt(0)
	v_mfma_f32_16x16x32_bf16 v[126:129], v[142:145], v[194:197], v[126:129]
	v_mfma_f32_16x16x32_bf16 v[126:129], v[182:185], v[198:201], v[126:129]
	v_mfma_f32_16x16x32_bf16 v[122:125], v[186:189], v[194:197], v[122:125]
	v_mfma_f32_16x16x32_bf16 v[122:125], v[190:193], v[198:201], v[122:125]
	v_mfma_f32_16x16x32_bf16 v[110:113], v[142:145], v[202:205], v[110:113]
	v_mfma_f32_16x16x32_bf16 v[110:113], v[182:185], v[206:209], v[110:113]
	v_mfma_f32_16x16x32_bf16 v[106:109], v[186:189], v[202:205], v[106:109]
	v_mfma_f32_16x16x32_bf16 v[106:109], v[190:193], v[206:209], v[106:109]
	v_mfma_f32_16x16x32_bf16 v[94:97], v[142:145], v[210:213], v[94:97]
	v_mfma_f32_16x16x32_bf16 v[94:97], v[182:185], v[214:217], v[94:97]
	v_mfma_f32_16x16x32_bf16 v[90:93], v[186:189], v[210:213], v[90:93]
	v_mfma_f32_16x16x32_bf16 v[90:93], v[190:193], v[214:217], v[90:93]
	v_mfma_f32_16x16x32_bf16 v[78:81], v[142:145], v[218:221], v[78:81]
	v_mfma_f32_16x16x32_bf16 v[78:81], v[182:185], v[222:225], v[78:81]
	v_mfma_f32_16x16x32_bf16 v[74:77], v[186:189], v[218:221], v[74:77]
	s_barrier
	v_mfma_f32_16x16x32_bf16 v[74:77], v[190:193], v[222:225], v[74:77]
	s_setprio 0
	s_add_i32 s51, 0, 0x1c000
	s_add_i32 s24, s39, s94
	v_add_u32_e32 v167, s51, v164
	s_add_i32 m0, s24, 0xffffff80
	ds_read_b128 v[226:229], v167
	ds_read_b128 v[230:233], v167 offset:1024
	ds_read_b128 v[234:237], v167 offset:2048
	ds_read_b128 v[238:241], v167 offset:3072
	global_load_lds_dwordx4 v134, s[48:49] offset:128
	s_add_i32 m0, s24, 0x1f80
	s_nop 0
	global_load_lds_dwordx4 v130, s[48:49] offset:128
	s_barrier
	s_waitcnt lgkmcnt(0)
	s_setprio 1
	s_waitcnt lgkmcnt(0)
	v_mfma_f32_16x16x32_bf16 v[118:121], v[226:229], v[194:197], v[118:121]
	v_mfma_f32_16x16x32_bf16 v[118:121], v[230:233], v[198:201], v[118:121]
	v_mfma_f32_16x16x32_bf16 v[114:117], v[234:237], v[194:197], v[114:117]
	v_mfma_f32_16x16x32_bf16 v[114:117], v[238:241], v[198:201], v[114:117]
	v_mfma_f32_16x16x32_bf16 v[102:105], v[226:229], v[202:205], v[102:105]
	v_mfma_f32_16x16x32_bf16 v[102:105], v[230:233], v[206:209], v[102:105]
	v_mfma_f32_16x16x32_bf16 v[98:101], v[234:237], v[202:205], v[98:101]
	v_mfma_f32_16x16x32_bf16 v[98:101], v[238:241], v[206:209], v[98:101]
	v_mfma_f32_16x16x32_bf16 v[86:89], v[226:229], v[210:213], v[86:89]
	v_mfma_f32_16x16x32_bf16 v[86:89], v[230:233], v[214:217], v[86:89]
	v_mfma_f32_16x16x32_bf16 v[82:85], v[234:237], v[210:213], v[82:85]
	v_mfma_f32_16x16x32_bf16 v[82:85], v[238:241], v[214:217], v[82:85]
	v_mfma_f32_16x16x32_bf16 v[70:73], v[226:229], v[218:221], v[70:73]
	v_mfma_f32_16x16x32_bf16 v[70:73], v[230:233], v[222:225], v[70:73]
	v_mfma_f32_16x16x32_bf16 v[66:69], v[234:237], v[218:221], v[66:69]
	s_barrier
; #define PG8_STAGE(bufoff, gbase, voff) do { _Pragma("unroll") for (int _i = 0; _i < 2; ++_i) \
;         __builtin_amdgcn_global_load_lds((const unsigned*)((const char*)(gbase) + (voff)[_i]), (LAS unsigned*)(lds + (bufoff) + ldsw + _i * 8192), 16, 0, 0); } while (0)
; #define PG8_LDA(dst, b, h) do { _Pragma("unroll") for (int m = 0; m < 4; ++m) _Pragma("unroll") for (int k = 0; k < 2; ++k) dst[m][k] = *(const LAS bf16x8*)(lds + PG8_SA(b, h) + aoff + m * 2048 + k * 1024); } while (0)
; #define PG8_MMA(ai, bj, At, Bt) do { __builtin_amdgcn_s_setprio(1); _Pragma("unroll") for (int m = 0; m < 4; ++m) _Pragma("unroll") for (int n = 0; n < 2; ++n) _Pragma("unroll") for (int k = 0; k < 2; ++k) \
;         acc[ai][bj][m][n] = __builtin_amdgcn_mfma_f32_16x16x32_bf16(Bt[n][k], At[m][k], acc[ai][bj][m][n], 0, 0, 0); __builtin_amdgcn_s_setprio(0); } while (0)
; #define PG8_WAIT_V(n) asm volatile("s_waitcnt vmcnt(" #n ")" ::: "memory")
; #define PG8_WAIT_L(n) asm volatile("s_waitcnt lgkmcnt(" #n ")" ::: "memory")
; #define PG8_BAR __builtin_amdgcn_s_barrier()
; #define PG8_SCHED __builtin_amdgcn_sched_barrier(0)
; template <class Epi, class Sched>
; __device__ __forceinline__ void gemm_phase(LAS unsigned char* lds, const Gemm g, const Sched& S, const Epi& E) {
;     ...
;             PG8_LDA(At, 1, 1); PG8_STAGE(PG8_SA(1, 0), a3, voffA);
;             PG8_BAR; PG8_WAIT_L(0); PG8_MMA(1, 0, At, B0); PG8_BAR; PG8_SCHED;
;             PG8_STAGE(PG8_SB(1, 1), b3 + hstep, voffB);
;             PG8_WAIT_V(6); PG8_BAR; PG8_MMA(1, 1, At, B1); PG8_BAR;
;         }
	v_mfma_f32_16x16x32_bf16 v[66:69], v[238:241], v[222:225], v[66:69]
	s_setprio 0
	s_add_i32 m0, s99, 0xffffff80
	ds_read_b128 v[194:197], v166 offset:49152
	ds_read_b128 v[198:201], v166 offset:50176
	ds_read_b128 v[202:205], v166 offset:51200
	ds_read_b128 v[206:209], v166 offset:52224
	ds_read_b128 v[210:213], v166 offset:53248
	ds_read_b128 v[214:217], v166 offset:54272
	ds_read_b128 v[218:221], v166 offset:55296
	ds_read_b128 v[222:225], v166 offset:56320
	global_load_lds_dwordx4 v136, vcc offset:128
	s_add_i32 m0, s82, 0xffffff80
	s_nop 0
	global_load_lds_dwordx4 v132, vcc offset:128
	s_waitcnt vmcnt(8)
	s_barrier
	s_waitcnt lgkmcnt(0)
	s_setprio 1
	s_waitcnt lgkmcnt(0)
	v_mfma_f32_16x16x32_bf16 v[62:65], v[142:145], v[194:197], v[62:65]
	v_mfma_f32_16x16x32_bf16 v[62:65], v[182:185], v[198:201], v[62:65]
	v_mfma_f32_16x16x32_bf16 v[58:61], v[186:189], v[194:197], v[58:61]
	v_mfma_f32_16x16x32_bf16 v[58:61], v[190:193], v[198:201], v[58:61]
	v_mfma_f32_16x16x32_bf16 v[46:49], v[142:145], v[202:205], v[46:49]
	v_mfma_f32_16x16x32_bf16 v[46:49], v[182:185], v[206:209], v[46:49]
	v_mfma_f32_16x16x32_bf16 v[42:45], v[186:189], v[202:205], v[42:45]
	v_mfma_f32_16x16x32_bf16 v[42:45], v[190:193], v[206:209], v[42:45]
	v_mfma_f32_16x16x32_bf16 v[30:33], v[142:145], v[210:213], v[30:33]
	v_mfma_f32_16x16x32_bf16 v[30:33], v[182:185], v[214:217], v[30:33]
	v_mfma_f32_16x16x32_bf16 v[26:29], v[186:189], v[210:213], v[26:29]
	v_mfma_f32_16x16x32_bf16 v[26:29], v[190:193], v[214:217], v[26:29]
	v_mfma_f32_16x16x32_bf16 v[14:17], v[142:145], v[218:221], v[14:17]
	v_mfma_f32_16x16x32_bf16 v[14:17], v[182:185], v[222:225], v[14:17]
	v_mfma_f32_16x16x32_bf16 v[10:13], v[186:189], v[218:221], v[10:13]
	s_barrier
	v_mfma_f32_16x16x32_bf16 v[10:13], v[190:193], v[222:225], v[10:13]
	s_setprio 0
	s_add_u32 s24, s48, 0x40080
	s_addc_u32 s25, s49, 0
	s_add_i32 s39, s51, s94
	s_mov_b32 m0, s39
	s_nop 0
	global_load_lds_dwordx4 v134, s[24:25]
	s_add_i32 m0, s39, 0x2000
	s_nop 0
	global_load_lds_dwordx4 v130, s[24:25]
	s_waitcnt vmcnt(6)
	s_barrier
	s_setprio 1
	v_add_u32_e32 v249, 0x10000, v164
	v_mfma_f32_16x16x32_bf16 v[54:57], v[226:229], v[194:197], v[54:57]
	ds_read_b128 v[142:145], v249
	ds_read_b128 v[182:185], v249 offset:1024
	v_mfma_f32_16x16x32_bf16 v[54:57], v[230:233], v[198:201], v[54:57]
	ds_read_b128 v[186:189], v249 offset:2048
	ds_read_b128 v[190:193], v249 offset:3072
	v_mfma_f32_16x16x32_bf16 v[50:53], v[234:237], v[194:197], v[50:53]
	ds_read_b128 v[194:197], v166
	v_mfma_f32_16x16x32_bf16 v[50:53], v[238:241], v[198:201], v[50:53]
	ds_read_b128 v[198:201], v166 offset:1024
	v_mfma_f32_16x16x32_bf16 v[38:41], v[226:229], v[202:205], v[38:41]
	v_mfma_f32_16x16x32_bf16 v[38:41], v[230:233], v[206:209], v[38:41]
	v_mfma_f32_16x16x32_bf16 v[34:37], v[234:237], v[202:205], v[34:37]
	ds_read_b128 v[202:205], v166 offset:2048
	v_mfma_f32_16x16x32_bf16 v[34:37], v[238:241], v[206:209], v[34:37]
	ds_read_b128 v[206:209], v166 offset:3072
	v_mfma_f32_16x16x32_bf16 v[22:25], v[226:229], v[210:213], v[22:25]
	v_mfma_f32_16x16x32_bf16 v[22:25], v[230:233], v[214:217], v[22:25]
	v_mfma_f32_16x16x32_bf16 v[18:21], v[234:237], v[210:213], v[18:21]
	ds_read_b128 v[210:213], v166 offset:4096
	v_mfma_f32_16x16x32_bf16 v[18:21], v[238:241], v[214:217], v[18:21]
	ds_read_b128 v[214:217], v166 offset:5120
	v_mfma_f32_16x16x32_bf16 v[6:9], v[226:229], v[218:221], v[6:9]
	v_mfma_f32_16x16x32_bf16 v[6:9], v[230:233], v[222:225], v[6:9]
	v_mfma_f32_16x16x32_bf16 v[2:5], v[234:237], v[218:221], v[2:5]
	s_barrier
	v_mfma_f32_16x16x32_bf16 v[2:5], v[238:241], v[222:225], v[2:5]
	s_setprio 0
	s_add_i32 s38, s38, 2
	s_add_u32 s35, s35, 0x100
	s_addc_u32 s50, s50, 0
	s_add_u32 s0, s0, 0x100
	s_addc_u32 s1, s1, 0
	s_cmp_gt_u32 s38, 13
	s_cbranch_scc0 .LBB0_557
	s_waitcnt lgkmcnt(0)
	s_and_b64 vcc, exec, s[42:43]
	s_cbranch_vccz .LBB0_560
	s_barrier

; #define PG8_STAGE(bufoff, gbase, voff) do { _Pragma("unroll") for (int _i = 0; _i < 2; ++_i) \
;         __builtin_amdgcn_global_load_lds((const unsigned*)((const char*)(gbase) + (voff)[_i]), (LAS unsigned*)(lds + (bufoff) + ldsw + _i * 8192), 16, 0, 0); } while (0)
; #define PG8_LDA(dst, b, h) do { _Pragma("unroll") for (int m = 0; m < 4; ++m) _Pragma("unroll") for (int k = 0; k < 2; ++k) dst[m][k] = *(const LAS bf16x8*)(lds + PG8_SA(b, h) + aoff + m * 2048 + k * 1024); } while (0)
; #define PG8_LDB(dst, b, h) do { _Pragma("unroll") for (int n = 0; n < 2; ++n) _Pragma("unroll") for (int k = 0; k < 2; ++k) dst[n][k] = *(const LAS bf16x8*)(lds + PG8_SB(b, h) + boff + n * 2048 + k * 1024); } while (0)
; #define PG8_MMA(ai, bj, At, Bt) do { __builtin_amdgcn_s_setprio(1); _Pragma("unroll") for (int m = 0; m < 4; ++m) _Pragma("unroll") for (int n = 0; n < 2; ++n) _Pragma("unroll") for (int k = 0; k < 2; ++k) \
;         acc[ai][bj][m][n] = __builtin_amdgcn_mfma_f32_16x16x32_bf16(Bt[n][k], At[m][k], acc[ai][bj][m][n], 0, 0, 0); __builtin_amdgcn_s_setprio(0); } while (0)
; #define PG8_WAIT_V(n) asm volatile("s_waitcnt vmcnt(" #n ")" ::: "memory")
; #define PG8_WAIT_L(n) asm volatile("s_waitcnt lgkmcnt(" #n ")" ::: "memory")
; #define PG8_BAR __builtin_amdgcn_s_barrier()
; template <class Epi, class Sched>
; __device__ __forceinline__ void gemm_phase(LAS unsigned char* lds, const Gemm g, const Sched& S, const Epi& E) {
;     ...
;             const bool last = (t == nt - 2);
;             const char* a1 = cA + (size_t)(t + 1) * kstep;
;             const char* a2 = last ? nA : cA + (size_t)(t + 2) * kstep; const char* b2 = last ? nB : cB + (size_t)(t + 2) * kstep;
;             const char* a3 = a2 + kstep; const char* b3 = b2 + kstep;
;             PG8_LDB(B0, 0, 0); PG8_SCHED; PG8_LDA(At, 0, 0); PG8_STAGE(PG8_SA(1, 1), a1 + hstep, voffA);
;             PG8_WAIT_L(8); PG8_BAR; PG8_WAIT_L(0); PG8_MMA(0, 0, At, B0); PG8_BAR; PG8_SCHED;
;             PG8_LDB(B1, 0, 1); PG8_STAGE(PG8_SB(0, 0), b2, voffB);
;             PG8_BAR; PG8_WAIT_L(0); PG8_MMA(0, 1, At, B1); PG8_BAR;
;             PG8_LDA(At, 0, 1); PG8_STAGE(PG8_SA(0, 0), a2, voffA);
;             PG8_BAR; PG8_WAIT_L(0); PG8_MMA(1, 0, At, B0); PG8_BAR; PG8_SCHED;
;             PG8_STAGE(PG8_SB(0, 1), b2 + hstep, voffB);
;             PG8_WAIT_V(6); PG8_BAR; PG8_MMA(1, 1, At, B1); PG8_BAR;
.LBB0_627:
	s_add_u32 s24, s0, 0xfff00080
	s_addc_u32 s25, s1, -1
	s_add_i32 s51, 0, 0x10000
	v_add_u32_e32 v142, s51, v144
	s_cmp_eq_u32 s98, 60
	s_cselect_b32 s77, s47, s25
	s_cselect_b32 s76, s46, s24
	s_cselect_b32 s49, s43, s50
	s_cselect_b32 s48, s45, s35
	s_add_i32 m0, s86, 0xc000
	ds_read_b128 v[218:221], v162 offset:6144
	ds_read_b128 v[222:225], v162 offset:7168
	global_load_lds_dwordx4 v140, s[0:1]
	s_add_i32 m0, s86, 0xe000
	s_nop 0
	global_load_lds_dwordx4 v138, s[0:1]
	s_waitcnt lgkmcnt(8)
	s_barrier
	s_waitcnt lgkmcnt(0)
	s_setprio 1
	s_waitcnt lgkmcnt(0)
	v_mfma_f32_16x16x32_bf16 v[126:129], v[164:167], v[194:197], v[126:129]
	v_mfma_f32_16x16x32_bf16 v[126:129], v[182:185], v[198:201], v[126:129]
	v_mfma_f32_16x16x32_bf16 v[122:125], v[186:189], v[194:197], v[122:125]
	v_mfma_f32_16x16x32_bf16 v[122:125], v[190:193], v[198:201], v[122:125]
	v_mfma_f32_16x16x32_bf16 v[118:121], v[164:167], v[202:205], v[118:121]
	v_mfma_f32_16x16x32_bf16 v[118:121], v[182:185], v[206:209], v[118:121]
	v_mfma_f32_16x16x32_bf16 v[110:113], v[186:189], v[202:205], v[110:113]
	v_mfma_f32_16x16x32_bf16 v[110:113], v[190:193], v[206:209], v[110:113]
	v_mfma_f32_16x16x32_bf16 v[102:105], v[164:167], v[210:213], v[102:105]
	v_mfma_f32_16x16x32_bf16 v[102:105], v[182:185], v[214:217], v[102:105]
	v_mfma_f32_16x16x32_bf16 v[94:97], v[186:189], v[210:213], v[94:97]
	v_mfma_f32_16x16x32_bf16 v[94:97], v[190:193], v[214:217], v[94:97]
	v_mfma_f32_16x16x32_bf16 v[86:89], v[164:167], v[218:221], v[86:89]
	v_mfma_f32_16x16x32_bf16 v[86:89], v[182:185], v[222:225], v[86:89]
	v_mfma_f32_16x16x32_bf16 v[78:81], v[186:189], v[218:221], v[78:81]
	s_barrier
	v_mfma_f32_16x16x32_bf16 v[78:81], v[190:193], v[222:225], v[78:81]
	s_setprio 0
	s_add_i32 s99, 0, 0x14000
	v_add_u32_e32 v142, s99, v144
	s_add_i32 s24, s51, s83
	ds_read_b128 v[226:229], v142
	ds_read_b128 v[230:233], v142 offset:1024
	ds_read_b128 v[234:237], v142 offset:2048
	ds_read_b128 v[238:241], v142 offset:3072
	s_mov_b32 m0, s24
	global_load_lds_dwordx4 v134, s[48:49]
	s_add_i32 m0, s24, 0x2000
	s_nop 0
	global_load_lds_dwordx4 v130, s[48:49]
	s_barrier
	s_waitcnt lgkmcnt(0)
	s_setprio 1
	s_waitcnt lgkmcnt(0)
	v_mfma_f32_16x16x32_bf16 v[114:117], v[226:229], v[194:197], v[114:117]
	v_mfma_f32_16x16x32_bf16 v[114:117], v[230:233], v[198:201], v[114:117]
	v_mfma_f32_16x16x32_bf16 v[106:109], v[234:237], v[194:197], v[106:109]
	v_mfma_f32_16x16x32_bf16 v[106:109], v[238:241], v[198:201], v[106:109]
	v_mfma_f32_16x16x32_bf16 v[98:101], v[226:229], v[202:205], v[98:101]
	v_mfma_f32_16x16x32_bf16 v[98:101], v[230:233], v[206:209], v[98:101]
	v_mfma_f32_16x16x32_bf16 v[90:93], v[234:237], v[202:205], v[90:93]
	v_mfma_f32_16x16x32_bf16 v[90:93], v[238:241], v[206:209], v[90:93]
	v_mfma_f32_16x16x32_bf16 v[82:85], v[226:229], v[210:213], v[82:85]
	v_mfma_f32_16x16x32_bf16 v[82:85], v[230:233], v[214:217], v[82:85]
	v_mfma_f32_16x16x32_bf16 v[74:77], v[234:237], v[210:213], v[74:77]
	v_mfma_f32_16x16x32_bf16 v[74:77], v[238:241], v[214:217], v[74:77]
	v_mfma_f32_16x16x32_bf16 v[70:73], v[226:229], v[218:221], v[70:73]
	v_mfma_f32_16x16x32_bf16 v[70:73], v[230:233], v[222:225], v[70:73]
	v_mfma_f32_16x16x32_bf16 v[66:69], v[234:237], v[218:221], v[66:69]
	s_barrier
	v_mfma_f32_16x16x32_bf16 v[66:69], v[238:241], v[222:225], v[66:69]
	s_setprio 0
	s_mov_b32 m0, s86
	s_mov_b64 s[100:101], s[76:77]
	ds_read_b128 v[194:197], v162 offset:16384
	ds_read_b128 v[198:201], v162 offset:17408
	ds_read_b128 v[202:205], v162 offset:18432
	ds_read_b128 v[206:209], v162 offset:19456
	ds_read_b128 v[210:213], v162 offset:20480
	ds_read_b128 v[214:217], v162 offset:21504
	ds_read_b128 v[218:221], v162 offset:22528
	ds_read_b128 v[222:225], v162 offset:23552
	global_load_lds_dwordx4 v136, s[76:77]
	s_mov_b64 s[100:101], s[76:77]
	s_mov_b32 m0, s92
	s_nop 0
	global_load_lds_dwordx4 v132, s[76:77]
	s_waitcnt vmcnt(8)
	s_barrier
	s_waitcnt lgkmcnt(0)
	s_setprio 1
	s_waitcnt lgkmcnt(0)
	v_mfma_f32_16x16x32_bf16 v[62:65], v[164:167], v[194:197], v[62:65]
	v_mfma_f32_16x16x32_bf16 v[62:65], v[182:185], v[198:201], v[62:65]
	v_mfma_f32_16x16x32_bf16 v[58:61], v[186:189], v[194:197], v[58:61]
	v_mfma_f32_16x16x32_bf16 v[58:61], v[190:193], v[198:201], v[58:61]
	v_mfma_f32_16x16x32_bf16 v[54:57], v[164:167], v[202:205], v[54:57]
	v_mfma_f32_16x16x32_bf16 v[54:57], v[182:185], v[206:209], v[54:57]
	v_mfma_f32_16x16x32_bf16 v[46:49], v[186:189], v[202:205], v[46:49]
	v_mfma_f32_16x16x32_bf16 v[46:49], v[190:193], v[206:209], v[46:49]
	v_mfma_f32_16x16x32_bf16 v[38:41], v[164:167], v[210:213], v[38:41]
	v_mfma_f32_16x16x32_bf16 v[38:41], v[182:185], v[214:217], v[38:41]
	v_mfma_f32_16x16x32_bf16 v[30:33], v[186:189], v[210:213], v[30:33]
	v_mfma_f32_16x16x32_bf16 v[30:33], v[190:193], v[214:217], v[30:33]
	v_mfma_f32_16x16x32_bf16 v[22:25], v[164:167], v[218:221], v[22:25]
	v_mfma_f32_16x16x32_bf16 v[22:25], v[182:185], v[222:225], v[22:25]
	v_mfma_f32_16x16x32_bf16 v[14:17], v[186:189], v[218:221], v[14:17]
	s_barrier
	v_mfma_f32_16x16x32_bf16 v[14:17], v[190:193], v[222:225], v[14:17]
	s_setprio 0
	s_add_u32 s24, s48, 0x100000
	s_addc_u32 s25, s49, 0
	s_add_i32 s51, s99, s83
	s_mov_b32 m0, s51
	s_nop 0
	global_load_lds_dwordx4 v134, s[24:25]
	s_add_i32 m0, s51, 0x2000
	s_nop 0
	global_load_lds_dwordx4 v130, s[24:25]
	s_waitcnt vmcnt(6)
	s_barrier
; #define PG8_STAGE(bufoff, gbase, voff) do { _Pragma("unroll") for (int _i = 0; _i < 2; ++_i) \
;         __builtin_amdgcn_global_load_lds((const unsigned*)((const char*)(gbase) + (voff)[_i]), (LAS unsigned*)(lds + (bufoff) + ldsw + _i * 8192), 16, 0, 0); } while (0)
; #define PG8_LDA(dst, b, h) do { _Pragma("unroll") for (int m = 0; m < 4; ++m) _Pragma("unroll") for (int k = 0; k < 2; ++k) dst[m][k] = *(const LAS bf16x8*)(lds + PG8_SA(b, h) + aoff + m * 2048 + k * 1024); } while (0)
; #define PG8_LDB(dst, b, h) do { _Pragma("unroll") for (int n = 0; n < 2; ++n) _Pragma("unroll") for (int k = 0; k < 2; ++k) dst[n][k] = *(const LAS bf16x8*)(lds + PG8_SB(b, h) + boff + n * 2048 + k * 1024); } while (0)
; #define PG8_MMA(ai, bj, At, Bt) do { __builtin_amdgcn_s_setprio(1); _Pragma("unroll") for (int m = 0; m < 4; ++m) _Pragma("unroll") for (int n = 0; n < 2; ++n) _Pragma("unroll") for (int k = 0; k < 2; ++k) \
;         acc[ai][bj][m][n] = __builtin_amdgcn_mfma_f32_16x16x32_bf16(Bt[n][k], At[m][k], acc[ai][bj][m][n], 0, 0, 0); __builtin_amdgcn_s_setprio(0); } while (0)
; #define PG8_WAIT_V(n) asm volatile("s_waitcnt vmcnt(" #n ")" ::: "memory")
; #define PG8_WAIT_L(n) asm volatile("s_waitcnt lgkmcnt(" #n ")" ::: "memory")
; #define PG8_BAR __builtin_amdgcn_s_barrier()
; #define PG8_SCHED __builtin_amdgcn_sched_barrier(0)
; template <class Epi, class Sched>
; __device__ __forceinline__ void gemm_phase(LAS unsigned char* lds, const Gemm g, const Sched& S, const Epi& E) {
;     ...
;             PG8_WAIT_V(6); PG8_BAR; PG8_MMA(1, 1, At, B1); PG8_BAR;
;             PG8_LDB(B0, 1, 0); PG8_SCHED; PG8_LDA(At, 1, 0); PG8_STAGE(PG8_SA(0, 1), a2 + hstep, voffA);
;             PG8_WAIT_L(8); PG8_BAR; PG8_WAIT_L(0); PG8_MMA(0, 0, At, B0); PG8_BAR; PG8_SCHED;
;             PG8_LDB(B1, 1, 1); PG8_STAGE(PG8_SB(1, 0), b3, voffB);
;             PG8_BAR; PG8_WAIT_L(0); PG8_MMA(0, 1, At, B1); PG8_BAR;
	s_setprio 1
	v_add_u32_e32 v249, 0x18000, v144
	v_mfma_f32_16x16x32_bf16 v[50:53], v[226:229], v[194:197], v[50:53]
	ds_read_b128 v[164:167], v249
	ds_read_b128 v[182:185], v249 offset:1024
	v_mfma_f32_16x16x32_bf16 v[50:53], v[230:233], v[198:201], v[50:53]
	ds_read_b128 v[186:189], v249 offset:2048
	ds_read_b128 v[190:193], v249 offset:3072
	v_mfma_f32_16x16x32_bf16 v[42:45], v[234:237], v[194:197], v[42:45]
	ds_read_b128 v[194:197], v162 offset:32768
	v_mfma_f32_16x16x32_bf16 v[42:45], v[238:241], v[198:201], v[42:45]
	ds_read_b128 v[198:201], v162 offset:33792
	v_mfma_f32_16x16x32_bf16 v[34:37], v[226:229], v[202:205], v[34:37]
	v_mfma_f32_16x16x32_bf16 v[34:37], v[230:233], v[206:209], v[34:37]
	v_mfma_f32_16x16x32_bf16 v[26:29], v[234:237], v[202:205], v[26:29]
	ds_read_b128 v[202:205], v162 offset:34816
	v_mfma_f32_16x16x32_bf16 v[26:29], v[238:241], v[206:209], v[26:29]
	ds_read_b128 v[206:209], v162 offset:35840
	v_mfma_f32_16x16x32_bf16 v[18:21], v[226:229], v[210:213], v[18:21]
	v_mfma_f32_16x16x32_bf16 v[18:21], v[230:233], v[214:217], v[18:21]
	v_mfma_f32_16x16x32_bf16 v[10:13], v[234:237], v[210:213], v[10:13]
	ds_read_b128 v[210:213], v162 offset:36864
	v_mfma_f32_16x16x32_bf16 v[10:13], v[238:241], v[214:217], v[10:13]
	ds_read_b128 v[214:217], v162 offset:37888
	v_mfma_f32_16x16x32_bf16 v[6:9], v[226:229], v[218:221], v[6:9]
	v_mfma_f32_16x16x32_bf16 v[6:9], v[230:233], v[222:225], v[6:9]
	v_mfma_f32_16x16x32_bf16 v[2:5], v[234:237], v[218:221], v[2:5]
	s_barrier
	v_mfma_f32_16x16x32_bf16 v[2:5], v[238:241], v[222:225], v[2:5]
	s_setprio 0
	s_add_i32 s51, 0, 0x18000
	v_add_u32_e32 v163, s51, v144
	s_add_u32 s24, s76, 0x100000
	s_addc_u32 s25, s77, 0
	s_mov_b32 m0, s93
	ds_read_b128 v[218:221], v162 offset:38912
	ds_read_b128 v[222:225], v162 offset:39936
	global_load_lds_dwordx4 v136, s[24:25]
	s_mov_b32 m0, s94
	s_nop 0
	global_load_lds_dwordx4 v132, s[24:25]
	s_waitcnt lgkmcnt(8)
	s_barrier
	s_waitcnt lgkmcnt(0)
	s_setprio 1
	s_waitcnt lgkmcnt(0)
	v_mfma_f32_16x16x32_bf16 v[126:129], v[164:167], v[194:197], v[126:129]
	v_mfma_f32_16x16x32_bf16 v[126:129], v[182:185], v[198:201], v[126:129]
	v_mfma_f32_16x16x32_bf16 v[122:125], v[186:189], v[194:197], v[122:125]
	v_mfma_f32_16x16x32_bf16 v[122:125], v[190:193], v[198:201], v[122:125]
	v_mfma_f32_16x16x32_bf16 v[118:121], v[164:167], v[202:205], v[118:121]
	v_mfma_f32_16x16x32_bf16 v[118:121], v[182:185], v[206:209], v[118:121]
	v_mfma_f32_16x16x32_bf16 v[110:113], v[186:189], v[202:205], v[110:113]
	v_mfma_f32_16x16x32_bf16 v[110:113], v[190:193], v[206:209], v[110:113]
	v_mfma_f32_16x16x32_bf16 v[102:105], v[164:167], v[210:213], v[102:105]
	v_mfma_f32_16x16x32_bf16 v[102:105], v[182:185], v[214:217], v[102:105]
	v_mfma_f32_16x16x32_bf16 v[94:97], v[186:189], v[210:213], v[94:97]
	v_mfma_f32_16x16x32_bf16 v[94:97], v[190:193], v[214:217], v[94:97]
	v_mfma_f32_16x16x32_bf16 v[86:89], v[164:167], v[218:221], v[86:89]
	v_mfma_f32_16x16x32_bf16 v[86:89], v[182:185], v[222:225], v[86:89]
	v_mfma_f32_16x16x32_bf16 v[78:81], v[186:189], v[218:221], v[78:81]
	s_barrier
	v_mfma_f32_16x16x32_bf16 v[78:81], v[190:193], v[222:225], v[78:81]
	s_setprio 0
	s_add_i32 s76, 0, 0x1c000
	s_add_i32 s24, s51, s83
	v_add_u32_e32 v163, s76, v144
	s_add_i32 m0, s24, 0xffffff80
	ds_read_b128 v[226:229], v163
	ds_read_b128 v[230:233], v163 offset:1024
	ds_read_b128 v[234:237], v163 offset:2048
	ds_read_b128 v[238:241], v163 offset:3072
	global_load_lds_dwordx4 v134, s[48:49] offset:128
	s_add_i32 m0, s24, 0x1f80
	s_nop 0
	global_load_lds_dwordx4 v130, s[48:49] offset:128
	s_barrier
	s_waitcnt lgkmcnt(0)
	s_setprio 1
	s_waitcnt lgkmcnt(0)
	v_mfma_f32_16x16x32_bf16 v[114:117], v[226:229], v[194:197], v[114:117]
	v_mfma_f32_16x16x32_bf16 v[114:117], v[230:233], v[198:201], v[114:117]
	v_mfma_f32_16x16x32_bf16 v[106:109], v[234:237], v[194:197], v[106:109]
	v_mfma_f32_16x16x32_bf16 v[106:109], v[238:241], v[198:201], v[106:109]
	v_mfma_f32_16x16x32_bf16 v[98:101], v[226:229], v[202:205], v[98:101]
	v_mfma_f32_16x16x32_bf16 v[98:101], v[230:233], v[206:209], v[98:101]
	v_mfma_f32_16x16x32_bf16 v[90:93], v[234:237], v[202:205], v[90:93]
	v_mfma_f32_16x16x32_bf16 v[90:93], v[238:241], v[206:209], v[90:93]
	v_mfma_f32_16x16x32_bf16 v[82:85], v[226:229], v[210:213], v[82:85]
	v_mfma_f32_16x16x32_bf16 v[82:85], v[230:233], v[214:217], v[82:85]
	v_mfma_f32_16x16x32_bf16 v[74:77], v[234:237], v[210:213], v[74:77]
	v_mfma_f32_16x16x32_bf16 v[74:77], v[238:241], v[214:217], v[74:77]
	v_mfma_f32_16x16x32_bf16 v[70:73], v[226:229], v[218:221], v[70:73]
	v_mfma_f32_16x16x32_bf16 v[70:73], v[230:233], v[222:225], v[70:73]
	v_mfma_f32_16x16x32_bf16 v[66:69], v[234:237], v[218:221], v[66:69]
	s_barrier
; #define PG8_STAGE(bufoff, gbase, voff) do { _Pragma("unroll") for (int _i = 0; _i < 2; ++_i) \
;         __builtin_amdgcn_global_load_lds((const unsigned*)((const char*)(gbase) + (voff)[_i]), (LAS unsigned*)(lds + (bufoff) + ldsw + _i * 8192), 16, 0, 0); } while (0)
; #define PG8_LDA(dst, b, h) do { _Pragma("unroll") for (int m = 0; m < 4; ++m) _Pragma("unroll") for (int k = 0; k < 2; ++k) dst[m][k] = *(const LAS bf16x8*)(lds + PG8_SA(b, h) + aoff + m * 2048 + k * 1024); } while (0)
; #define PG8_MMA(ai, bj, At, Bt) do { __builtin_amdgcn_s_setprio(1); _Pragma("unroll") for (int m = 0; m < 4; ++m) _Pragma("unroll") for (int n = 0; n < 2; ++n) _Pragma("unroll") for (int k = 0; k < 2; ++k) \
;         acc[ai][bj][m][n] = __builtin_amdgcn_mfma_f32_16x16x32_bf16(Bt[n][k], At[m][k], acc[ai][bj][m][n], 0, 0, 0); __builtin_amdgcn_s_setprio(0); } while (0)
; #define PG8_WAIT_V(n) asm volatile("s_waitcnt vmcnt(" #n ")" ::: "memory")
; #define PG8_WAIT_L(n) asm volatile("s_waitcnt lgkmcnt(" #n ")" ::: "memory")
; #define PG8_BAR __builtin_amdgcn_s_barrier()
; #define PG8_SCHED __builtin_amdgcn_sched_barrier(0)
; template <class Epi, class Sched>
; __device__ __forceinline__ void gemm_phase(LAS unsigned char* lds, const Gemm g, const Sched& S, const Epi& E) {
;     ...
;             PG8_LDA(At, 1, 1); PG8_STAGE(PG8_SA(1, 0), a3, voffA);
;             PG8_BAR; PG8_WAIT_L(0); PG8_MMA(1, 0, At, B0); PG8_BAR; PG8_SCHED;
;             PG8_STAGE(PG8_SB(1, 1), b3 + hstep, voffB);
;             PG8_WAIT_V(6); PG8_BAR; PG8_MMA(1, 1, At, B1); PG8_BAR;
;         }
	v_mfma_f32_16x16x32_bf16 v[66:69], v[238:241], v[222:225], v[66:69]
	s_setprio 0
	s_add_i32 m0, s95, 0xffffff80
	ds_read_b128 v[194:197], v162 offset:49152
	ds_read_b128 v[198:201], v162 offset:50176
	ds_read_b128 v[202:205], v162 offset:51200
	ds_read_b128 v[206:209], v162 offset:52224
	ds_read_b128 v[210:213], v162 offset:53248
	ds_read_b128 v[214:217], v162 offset:54272
	ds_read_b128 v[218:221], v162 offset:55296
	ds_read_b128 v[222:225], v162 offset:56320
	global_load_lds_dwordx4 v136, s[100:101] offset:128
	s_add_i32 m0, s96, 0xffffff80
	s_nop 0
	global_load_lds_dwordx4 v132, s[100:101] offset:128
	s_waitcnt vmcnt(8)
	s_barrier
	s_waitcnt lgkmcnt(0)
	s_setprio 1
	s_waitcnt lgkmcnt(0)
	v_mfma_f32_16x16x32_bf16 v[62:65], v[164:167], v[194:197], v[62:65]
	v_mfma_f32_16x16x32_bf16 v[62:65], v[182:185], v[198:201], v[62:65]
	v_mfma_f32_16x16x32_bf16 v[58:61], v[186:189], v[194:197], v[58:61]
	v_mfma_f32_16x16x32_bf16 v[58:61], v[190:193], v[198:201], v[58:61]
	v_mfma_f32_16x16x32_bf16 v[54:57], v[164:167], v[202:205], v[54:57]
	v_mfma_f32_16x16x32_bf16 v[54:57], v[182:185], v[206:209], v[54:57]
	v_mfma_f32_16x16x32_bf16 v[46:49], v[186:189], v[202:205], v[46:49]
	v_mfma_f32_16x16x32_bf16 v[46:49], v[190:193], v[206:209], v[46:49]
	v_mfma_f32_16x16x32_bf16 v[38:41], v[164:167], v[210:213], v[38:41]
	v_mfma_f32_16x16x32_bf16 v[38:41], v[182:185], v[214:217], v[38:41]
	v_mfma_f32_16x16x32_bf16 v[30:33], v[186:189], v[210:213], v[30:33]
	v_mfma_f32_16x16x32_bf16 v[30:33], v[190:193], v[214:217], v[30:33]
	v_mfma_f32_16x16x32_bf16 v[22:25], v[164:167], v[218:221], v[22:25]
	v_mfma_f32_16x16x32_bf16 v[22:25], v[182:185], v[222:225], v[22:25]
	v_mfma_f32_16x16x32_bf16 v[14:17], v[186:189], v[218:221], v[14:17]
	s_barrier
	v_mfma_f32_16x16x32_bf16 v[14:17], v[190:193], v[222:225], v[14:17]
	s_setprio 0
	s_add_u32 s24, s48, 0x100080
	s_addc_u32 s25, s49, 0
	s_add_i32 s48, s76, s83
	s_mov_b32 m0, s48
	s_nop 0
	global_load_lds_dwordx4 v134, s[24:25]
	s_add_i32 m0, s48, 0x2000
	s_nop 0
	global_load_lds_dwordx4 v130, s[24:25]
	s_waitcnt vmcnt(6)
	s_barrier
	s_setprio 1
	v_add_u32_e32 v249, 0x10000, v144
	v_mfma_f32_16x16x32_bf16 v[50:53], v[226:229], v[194:197], v[50:53]
	ds_read_b128 v[164:167], v249
	ds_read_b128 v[182:185], v249 offset:1024
	v_mfma_f32_16x16x32_bf16 v[50:53], v[230:233], v[198:201], v[50:53]
	ds_read_b128 v[186:189], v249 offset:2048
	ds_read_b128 v[190:193], v249 offset:3072
	v_mfma_f32_16x16x32_bf16 v[42:45], v[234:237], v[194:197], v[42:45]
	ds_read_b128 v[194:197], v162
	v_mfma_f32_16x16x32_bf16 v[42:45], v[238:241], v[198:201], v[42:45]
	ds_read_b128 v[198:201], v162 offset:1024
	v_mfma_f32_16x16x32_bf16 v[34:37], v[226:229], v[202:205], v[34:37]
	v_mfma_f32_16x16x32_bf16 v[34:37], v[230:233], v[206:209], v[34:37]
	v_mfma_f32_16x16x32_bf16 v[26:29], v[234:237], v[202:205], v[26:29]
	ds_read_b128 v[202:205], v162 offset:2048
	v_mfma_f32_16x16x32_bf16 v[26:29], v[238:241], v[206:209], v[26:29]
	ds_read_b128 v[206:209], v162 offset:3072
	v_mfma_f32_16x16x32_bf16 v[18:21], v[226:229], v[210:213], v[18:21]
	v_mfma_f32_16x16x32_bf16 v[18:21], v[230:233], v[214:217], v[18:21]
	v_mfma_f32_16x16x32_bf16 v[10:13], v[234:237], v[210:213], v[10:13]
	ds_read_b128 v[210:213], v162 offset:4096
	v_mfma_f32_16x16x32_bf16 v[10:13], v[238:241], v[214:217], v[10:13]
	ds_read_b128 v[214:217], v162 offset:5120
	v_mfma_f32_16x16x32_bf16 v[6:9], v[226:229], v[218:221], v[6:9]
	v_mfma_f32_16x16x32_bf16 v[6:9], v[230:233], v[222:225], v[6:9]
	v_mfma_f32_16x16x32_bf16 v[2:5], v[234:237], v[218:221], v[2:5]
	s_barrier
	v_mfma_f32_16x16x32_bf16 v[2:5], v[238:241], v[222:225], v[2:5]
	s_setprio 0
	s_add_i32 s98, s98, 2
	s_add_u32 s35, s35, 0x100
	s_addc_u32 s50, s50, 0
	s_add_u32 s0, s0, 0x100
	s_addc_u32 s1, s1, 0
	s_cmp_gt_u32 s98, 61
	s_cbranch_scc0 .LBB0_627
	s_waitcnt lgkmcnt(0)
	s_and_b64 vcc, exec, s[40:41]
	s_cbranch_vccz .LBB0_630
	s_barrier

; __global__ void __launch_bounds__(NTHREADS, 2) fwd_megakernel(Params P) {
	.amdhsa_kernel _Z14fwd_megakernel6Params
		.amdhsa_group_segment_fixed_size 0
		.amdhsa_private_segment_fixed_size 0
		.amdhsa_kernarg_size 376
		.amdhsa_user_sgpr_count 2
		.amdhsa_user_sgpr_dispatch_ptr 0
		.amdhsa_user_sgpr_queue_ptr 0
		.amdhsa_user_sgpr_kernarg_segment_ptr 1
		.amdhsa_user_sgpr_dispatch_id 0
		.amdhsa_user_sgpr_kernarg_preload_length 0
		.amdhsa_user_sgpr_kernarg_preload_offset 0
		.amdhsa_user_sgpr_private_segment_size 0
		.amdhsa_uses_dynamic_stack 0
		.amdhsa_enable_private_segment 0
		.amdhsa_system_sgpr_workgroup_id_x 1
		.amdhsa_system_sgpr_workgroup_id_y 0
		.amdhsa_system_sgpr_workgroup_id_z 0
		.amdhsa_system_sgpr_workgroup_info 0
		.amdhsa_system_vgpr_workitem_id 2
		.amdhsa_next_free_vgpr 256
		.amdhsa_next_free_sgpr 102
		.amdhsa_accum_offset 256
		.amdhsa_reserve_vcc 1
		.amdhsa_float_round_mode_32 0
		.amdhsa_float_round_mode_16_64 0
		.amdhsa_float_denorm_mode_32 3
		.amdhsa_float_denorm_mode_16_64 3
		.amdhsa_dx10_clamp 1
		.amdhsa_ieee_mode 1
		.amdhsa_fp16_overflow 0
		.amdhsa_tg_split 0
		.amdhsa_exception_fp_ieee_invalid_op 0
		.amdhsa_exception_fp_denorm_src 0
		.amdhsa_exception_fp_ieee_div_zero 0
		.amdhsa_exception_fp_ieee_overflow 0
		.amdhsa_exception_fp_ieee_underflow 0
		.amdhsa_exception_fp_ieee_inexact 0
		.amdhsa_exception_int_div_zero 0
	.end_amdhsa_kernel

; __global__ void __launch_bounds__(NTHREADS, 2) fwd_megakernel(Params P) {
amdhsa.kernels:
  - .agpr_count:     0
    .args:
      - .offset:         0
        .size:           120
        .value_kind:     by_value
      - .offset:         120
        .size:           4
        .value_kind:     hidden_block_count_x
      - .offset:         124
        .size:           4
        .value_kind:     hidden_block_count_y
      - .offset:         128
        .size:           4
        .value_kind:     hidden_block_count_z
      - .offset:         132
        .size:           2
        .value_kind:     hidden_group_size_x
      - .offset:         134
        .size:           2
        .value_kind:     hidden_group_size_y
      - .offset:         136
        .size:           2
        .value_kind:     hidden_group_size_z
      - .offset:         138
        .size:           2
        .value_kind:     hidden_remainder_x
      - .offset:         140
        .size:           2
        .value_kind:     hidden_remainder_y
      - .offset:         142
        .size:           2
        .value_kind:     hidden_remainder_z
      - .offset:         160
        .size:           8
        .value_kind:     hidden_global_offset_x
      - .offset:         168
        .size:           8
        .value_kind:     hidden_global_offset_y
      - .offset:         176
        .size:           8
        .value_kind:     hidden_global_offset_z
      - .offset:         184
        .size:           2
        .value_kind:     hidden_grid_dims
      - .offset:         208
        .size:           8
        .value_kind:     hidden_multigrid_sync_arg
      - .offset:         240
        .size:           4
        .value_kind:     hidden_dynamic_lds_size
    .group_segment_fixed_size: 0
    .kernarg_segment_align: 8
    .kernarg_segment_size: 376
    .language:       OpenCL C
    .language_version:
      - 2
      - 0
    .max_flat_workgroup_size: 512
    .name:           _Z14fwd_megakernel6Params
    .private_segment_fixed_size: 0
    .sgpr_count:     108
    .sgpr_spill_count: 151
    .symbol:         _Z14fwd_megakernel6Params.kd
    .uniform_work_group_size: 1
    .uses_dynamic_stack: false
    .vgpr_count:     256
    .vgpr_spill_count: 0
    .wavefront_size: 64
